# GEMM K-loops: back-to-back s_setprio 0/1 pairs between MFMA groups removed
# speedup vs baseline: 1.0083x; 1.0083x over previous
; #define PG8_STAGE(bufoff, gbase, voff) do { _Pragma("unroll") for (int _i = 0; _i < 2; ++_i) \
;         __builtin_amdgcn_global_load_lds((const unsigned*)((const char*)(gbase) + (voff)[_i]), (PG8_LAS unsigned*)(lds + (bufoff) + ldsw + _i * 8192), 16, 0, 0); } while (0)
; #define PG8_LDA(dst, b, h) do { _Pragma("unroll") for (int m = 0; m < 4; ++m) _Pragma("unroll") for (int k = 0; k < 2; ++k) dst[m][k] = *(const PG8_LAS bf16x8*)(lds + PG8_SA(b, h) + aoff + m * 2048 + k * 1024); } while (0)
; #define PG8_LDB(dst, b, h) do { _Pragma("unroll") for (int n = 0; n < 2; ++n) _Pragma("unroll") for (int k = 0; k < 2; ++k) dst[n][k] = *(const PG8_LAS bf16x8*)(lds + PG8_SB(b, h) + boff + n * 2048 + k * 1024); } while (0)
; #define PG8_MMA(ai, bj, At, Bt) do { __builtin_amdgcn_s_setprio(1); _Pragma("unroll") for (int m = 0; m < 4; ++m) _Pragma("unroll") for (int n = 0; n < 2; ++n) _Pragma("unroll") for (int k = 0; k < 2; ++k) \
;         acc[ai][bj][m][n] = mma16<F16>(Bt[n][k], At[m][k], acc[ai][bj][m][n]); __builtin_amdgcn_s_setprio(0); } while (0)
; #define PG8_WAIT_V(n) asm volatile("s_waitcnt vmcnt(" #n ")" ::: "memory")
; #define PG8_WAIT_L(n) asm volatile("s_waitcnt lgkmcnt(" #n ")" ::: "memory")
; #define PG8_BAR __builtin_amdgcn_s_barrier()
; #define PG8_SCHED __builtin_amdgcn_sched_barrier(0)
; template <class Epi, class Sched, bool ALIGN_EPI = false, bool SP2 = false, bool F16 = false>
; __device__ __forceinline__ void gemm_phase(PG8_LAS unsigned char* lds, const Gemm g, const Sched& S, const Epi& E) {
;     ...
;             PG8_LDB(B0, 0, 0); PG8_LDB(B1, 0, 1); PG8_SCHED; PG8_LDA(At, 0, 0); PG8_STAGE(PG8_SA(1, 1), a1 + hstep, voffA);
;             PG8_WAIT_V(8); PG8_WAIT_L(0); PG8_BAR; PG8_MMA(0, 0, At, B0); PG8_MMA(0, 1, At, B1); PG8_BAR; PG8_SCHED;
;             PG8_LDA(At, 0, 1); PG8_STAGE(PG8_SB(0, 0), b2, voffB); PG8_STAGE(PG8_SB(0, 1), b2 + hstep, voffB); PG8_STAGE(PG8_SA(0, 0), a2, voffA);
;             PG8_WAIT_V(8); PG8_WAIT_L(0); PG8_BAR; PG8_MMA(1, 0, At, B0); PG8_MMA(1, 1, At, B1); PG8_BAR; PG8_SCHED;
.LBB0_256:
	s_add_u32 s42, s0, 0xfffc0080
	s_addc_u32 s43, s1, -1
	s_add_i32 s68, 0, 0x10000
	s_cmp_eq_u32 s67, 12
	s_cselect_b32 s55, s4, s43
	s_cselect_b32 s54, s5, s42
	s_cselect_b32 s43, s7, s61
	s_cselect_b32 s42, s34, s59
	s_add_i32 s70, 0, 0x14000
	ds_read_b128 v[130:133], v242
	ds_read_b128 v[134:137], v242 offset:1024
	ds_read_b128 v[138:141], v242 offset:2048
	ds_read_b128 v[162:165], v242 offset:3072
	ds_read_b128 v[166:169], v242 offset:16384
	ds_read_b128 v[170:173], v242 offset:17408
	ds_read_b128 v[186:189], v242 offset:18432
	ds_read_b128 v[190:193], v242 offset:19456
	s_add_i32 m0, s21, 0xc000
	ds_read_b128 v[194:197], v240
	ds_read_b128 v[198:201], v240 offset:1024
	ds_read_b128 v[202:205], v240 offset:2048
	ds_read_b128 v[206:209], v240 offset:3072
	ds_read_b128 v[210:213], v240 offset:4096
	ds_read_b128 v[214:217], v240 offset:5120
	ds_read_b128 v[218:221], v240 offset:6144
	ds_read_b128 v[222:225], v240 offset:7168
	global_load_lds_dwordx4 v154, s[0:1]
	s_add_i32 m0, s21, 0xe000
	s_nop 0
	global_load_lds_dwordx4 v156, s[0:1]
	s_waitcnt vmcnt(8)
	s_waitcnt lgkmcnt(0)
	s_barrier
	s_setprio 1
	s_waitcnt lgkmcnt(0)
	v_mfma_f32_16x16x32_f16 v[124:127], v[130:133], v[194:197], v[124:127]
	v_mfma_f32_16x16x32_f16 v[120:123], v[138:141], v[194:197], v[120:123]
	v_mfma_f32_16x16x32_f16 v[116:119], v[130:133], v[202:205], v[116:119]
	v_mfma_f32_16x16x32_f16 v[112:115], v[138:141], v[202:205], v[112:115]
	v_mfma_f32_16x16x32_f16 v[108:111], v[130:133], v[210:213], v[108:111]
	v_mfma_f32_16x16x32_f16 v[104:107], v[138:141], v[210:213], v[104:107]
	v_mfma_f32_16x16x32_f16 v[100:103], v[130:133], v[218:221], v[100:103]
	v_mfma_f32_16x16x32_f16 v[96:99], v[138:141], v[218:221], v[96:99]
	v_mfma_f32_16x16x32_f16 v[124:127], v[134:137], v[198:201], v[124:127]
	v_mfma_f32_16x16x32_f16 v[120:123], v[162:165], v[198:201], v[120:123]
	v_mfma_f32_16x16x32_f16 v[116:119], v[134:137], v[206:209], v[116:119]
	v_mfma_f32_16x16x32_f16 v[112:115], v[162:165], v[206:209], v[112:115]
	v_mfma_f32_16x16x32_f16 v[108:111], v[134:137], v[214:217], v[108:111]
	v_mfma_f32_16x16x32_f16 v[104:107], v[162:165], v[214:217], v[104:107]
	v_mfma_f32_16x16x32_f16 v[100:103], v[134:137], v[222:225], v[100:103]
	v_mfma_f32_16x16x32_f16 v[96:99], v[162:165], v[222:225], v[96:99]
	v_mfma_f32_16x16x32_f16 v[60:63], v[166:169], v[194:197], v[60:63]
	v_mfma_f32_16x16x32_f16 v[56:59], v[186:189], v[194:197], v[56:59]
	v_mfma_f32_16x16x32_f16 v[52:55], v[166:169], v[202:205], v[52:55]
	v_mfma_f32_16x16x32_f16 v[48:51], v[186:189], v[202:205], v[48:51]
	v_mfma_f32_16x16x32_f16 v[44:47], v[166:169], v[210:213], v[44:47]
	v_mfma_f32_16x16x32_f16 v[40:43], v[186:189], v[210:213], v[40:43]
	v_mfma_f32_16x16x32_f16 v[36:39], v[166:169], v[218:221], v[36:39]
	v_mfma_f32_16x16x32_f16 v[32:35], v[186:189], v[218:221], v[32:35]
	v_mfma_f32_16x16x32_f16 v[60:63], v[170:173], v[198:201], v[60:63]
	v_mfma_f32_16x16x32_f16 v[56:59], v[190:193], v[198:201], v[56:59]
	v_mfma_f32_16x16x32_f16 v[52:55], v[170:173], v[206:209], v[52:55]
	v_mfma_f32_16x16x32_f16 v[48:51], v[190:193], v[206:209], v[48:51]
	v_mfma_f32_16x16x32_f16 v[44:47], v[170:173], v[214:217], v[44:47]
	v_mfma_f32_16x16x32_f16 v[40:43], v[190:193], v[214:217], v[40:43]
	v_mfma_f32_16x16x32_f16 v[36:39], v[170:173], v[222:225], v[36:39]
	v_mfma_f32_16x16x32_f16 v[32:35], v[190:193], v[222:225], v[32:35]
	s_setprio 0
	s_barrier
	s_add_u32 s98, s42, s16
	s_addc_u32 s99, s43, s17
	s_add_u32 s100, s54, s16
	s_addc_u32 s101, s55, s17
	s_add_i32 s68, s68, s20
	s_mov_b32 m0, s68
	ds_read_b128 v[194:197], v240 offset:16384
	ds_read_b128 v[198:201], v240 offset:17408
	ds_read_b128 v[202:205], v240 offset:18432
	ds_read_b128 v[206:209], v240 offset:19456
	ds_read_b128 v[210:213], v240 offset:20480
	ds_read_b128 v[214:217], v240 offset:21504
	ds_read_b128 v[218:221], v240 offset:22528
	ds_read_b128 v[222:225], v240 offset:23552
	global_load_lds_dwordx4 v146, s[42:43]
	s_add_i32 m0, s68, 0x2000
	s_add_u32 s68, s42, 0x40000
	s_addc_u32 s69, s43, 0
	s_add_i32 s70, s70, s20
	global_load_lds_dwordx4 v142, s[42:43]
	s_mov_b32 m0, s70
	s_nop 0
	global_load_lds_dwordx4 v146, s[68:69]
	s_add_i32 m0, s70, 0x2000
	s_nop 0
	global_load_lds_dwordx4 v142, s[68:69]
	s_mov_b32 m0, s21
	s_nop 0
	global_load_lds_dwordx4 v148, s[54:55]
	s_mov_b32 m0, s14
	s_nop 0
	global_load_lds_dwordx4 v144, s[54:55]
	s_waitcnt vmcnt(8)
	s_waitcnt lgkmcnt(0)
	s_barrier
	s_setprio 1
	s_waitcnt lgkmcnt(0)
	v_mfma_f32_16x16x32_f16 v[92:95], v[130:133], v[194:197], v[92:95]
	v_mfma_f32_16x16x32_f16 v[88:91], v[138:141], v[194:197], v[88:91]
	v_mfma_f32_16x16x32_f16 v[84:87], v[130:133], v[202:205], v[84:87]
	v_mfma_f32_16x16x32_f16 v[80:83], v[138:141], v[202:205], v[80:83]
	v_mfma_f32_16x16x32_f16 v[76:79], v[130:133], v[210:213], v[76:79]
	v_mfma_f32_16x16x32_f16 v[72:75], v[138:141], v[210:213], v[72:75]
	v_mfma_f32_16x16x32_f16 v[68:71], v[130:133], v[218:221], v[68:71]
	v_mfma_f32_16x16x32_f16 v[64:67], v[138:141], v[218:221], v[64:67]
	v_mfma_f32_16x16x32_f16 v[92:95], v[134:137], v[198:201], v[92:95]
	v_mfma_f32_16x16x32_f16 v[88:91], v[162:165], v[198:201], v[88:91]
	v_mfma_f32_16x16x32_f16 v[84:87], v[134:137], v[206:209], v[84:87]
	v_mfma_f32_16x16x32_f16 v[80:83], v[162:165], v[206:209], v[80:83]
	v_mfma_f32_16x16x32_f16 v[76:79], v[134:137], v[214:217], v[76:79]
	v_mfma_f32_16x16x32_f16 v[72:75], v[162:165], v[214:217], v[72:75]
	v_mfma_f32_16x16x32_f16 v[68:71], v[134:137], v[222:225], v[68:71]
	v_mfma_f32_16x16x32_f16 v[64:67], v[162:165], v[222:225], v[64:67]
	v_mfma_f32_16x16x32_f16 v[28:31], v[166:169], v[194:197], v[28:31]
	v_mfma_f32_16x16x32_f16 v[24:27], v[186:189], v[194:197], v[24:27]
	v_mfma_f32_16x16x32_f16 v[20:23], v[166:169], v[202:205], v[20:23]
	v_mfma_f32_16x16x32_f16 v[16:19], v[186:189], v[202:205], v[16:19]
	v_mfma_f32_16x16x32_f16 v[12:15], v[166:169], v[210:213], v[12:15]
	v_mfma_f32_16x16x32_f16 v[8:11], v[186:189], v[210:213], v[8:11]
	v_mfma_f32_16x16x32_f16 v[4:7], v[166:169], v[218:221], v[4:7]
	v_mfma_f32_16x16x32_f16 v[0:3], v[186:189], v[218:221], v[0:3]
	v_mfma_f32_16x16x32_f16 v[28:31], v[170:173], v[198:201], v[28:31]
	v_mfma_f32_16x16x32_f16 v[24:27], v[190:193], v[198:201], v[24:27]
	v_mfma_f32_16x16x32_f16 v[20:23], v[170:173], v[206:209], v[20:23]
	v_mfma_f32_16x16x32_f16 v[16:19], v[190:193], v[206:209], v[16:19]
	v_mfma_f32_16x16x32_f16 v[12:15], v[170:173], v[214:217], v[12:15]
	v_mfma_f32_16x16x32_f16 v[8:11], v[190:193], v[214:217], v[8:11]
	v_mfma_f32_16x16x32_f16 v[4:7], v[170:173], v[222:225], v[4:7]
	v_mfma_f32_16x16x32_f16 v[0:3], v[190:193], v[222:225], v[0:3]
	s_setprio 0
	s_barrier
; #define PG8_STAGE(bufoff, gbase, voff) do { _Pragma("unroll") for (int _i = 0; _i < 2; ++_i) \
;         __builtin_amdgcn_global_load_lds((const unsigned*)((const char*)(gbase) + (voff)[_i]), (PG8_LAS unsigned*)(lds + (bufoff) + ldsw + _i * 8192), 16, 0, 0); } while (0)
; #define PG8_LDA(dst, b, h) do { _Pragma("unroll") for (int m = 0; m < 4; ++m) _Pragma("unroll") for (int k = 0; k < 2; ++k) dst[m][k] = *(const PG8_LAS bf16x8*)(lds + PG8_SA(b, h) + aoff + m * 2048 + k * 1024); } while (0)
; #define PG8_LDB(dst, b, h) do { _Pragma("unroll") for (int n = 0; n < 2; ++n) _Pragma("unroll") for (int k = 0; k < 2; ++k) dst[n][k] = *(const PG8_LAS bf16x8*)(lds + PG8_SB(b, h) + boff + n * 2048 + k * 1024); } while (0)
; #define PG8_MMA(ai, bj, At, Bt) do { __builtin_amdgcn_s_setprio(1); _Pragma("unroll") for (int m = 0; m < 4; ++m) _Pragma("unroll") for (int n = 0; n < 2; ++n) _Pragma("unroll") for (int k = 0; k < 2; ++k) \
;         acc[ai][bj][m][n] = mma16<F16>(Bt[n][k], At[m][k], acc[ai][bj][m][n]); __builtin_amdgcn_s_setprio(0); } while (0)
; #define PG8_WAIT_V(n) asm volatile("s_waitcnt vmcnt(" #n ")" ::: "memory")
; #define PG8_WAIT_L(n) asm volatile("s_waitcnt lgkmcnt(" #n ")" ::: "memory")
; #define PG8_BAR __builtin_amdgcn_s_barrier()
; #define PG8_SCHED __builtin_amdgcn_sched_barrier(0)
; template <class Epi, class Sched, bool ALIGN_EPI = false, bool SP2 = false, bool F16 = false>
; __device__ __forceinline__ void gemm_phase(PG8_LAS unsigned char* lds, const Gemm g, const Sched& S, const Epi& E) {
;     ...
;             PG8_LDB(B0, 1, 0); PG8_LDB(B1, 1, 1); PG8_SCHED; PG8_LDA(At, 1, 0); PG8_STAGE(PG8_SA(0, 1), a2 + hstep, voffA);
;             PG8_WAIT_V(8); PG8_WAIT_L(0); PG8_BAR; PG8_MMA(0, 0, At, B0); PG8_MMA(0, 1, At, B1); PG8_BAR; PG8_SCHED;
;             PG8_LDA(At, 1, 1); PG8_STAGE(PG8_SB(1, 0), b3, voffB); PG8_STAGE(PG8_SB(1, 1), b3 + hstep, voffB); PG8_STAGE(PG8_SA(1, 0), a3, voffA);
;             PG8_WAIT_V(8); PG8_WAIT_L(0); PG8_BAR; PG8_MMA(1, 0, At, B0); PG8_MMA(1, 1, At, B1); PG8_BAR; PG8_SCHED;
	s_add_i32 s68, 0, 0x18000
	s_add_i32 s69, 0, 0x1c000
	ds_read_b128 v[130:133], v242 offset:32768
	ds_read_b128 v[134:137], v242 offset:33792
	ds_read_b128 v[138:141], v242 offset:34816
	ds_read_b128 v[162:165], v242 offset:35840
	ds_read_b128 v[166:169], v242 offset:49152
	ds_read_b128 v[170:173], v242 offset:50176
	ds_read_b128 v[186:189], v242 offset:51200
	ds_read_b128 v[190:193], v242 offset:52224
	s_add_u32 s54, s54, 0x40000
	s_addc_u32 s55, s55, 0
	s_mov_b32 m0, s15
	ds_read_b128 v[194:197], v240 offset:32768
	ds_read_b128 v[198:201], v240 offset:33792
	ds_read_b128 v[202:205], v240 offset:34816
	ds_read_b128 v[206:209], v240 offset:35840
	ds_read_b128 v[210:213], v240 offset:36864
	ds_read_b128 v[214:217], v240 offset:37888
	ds_read_b128 v[218:221], v240 offset:38912
	ds_read_b128 v[222:225], v240 offset:39936
	global_load_lds_dwordx4 v148, s[54:55]
	s_mov_b32 m0, s37
	s_nop 0
	global_load_lds_dwordx4 v144, s[54:55]
	s_waitcnt vmcnt(8)
	s_waitcnt lgkmcnt(0)
	s_barrier
	s_setprio 1
	s_waitcnt lgkmcnt(0)
	v_mfma_f32_16x16x32_f16 v[124:127], v[130:133], v[194:197], v[124:127]
	v_mfma_f32_16x16x32_f16 v[120:123], v[138:141], v[194:197], v[120:123]
	v_mfma_f32_16x16x32_f16 v[116:119], v[130:133], v[202:205], v[116:119]
	v_mfma_f32_16x16x32_f16 v[112:115], v[138:141], v[202:205], v[112:115]
	v_mfma_f32_16x16x32_f16 v[108:111], v[130:133], v[210:213], v[108:111]
	v_mfma_f32_16x16x32_f16 v[104:107], v[138:141], v[210:213], v[104:107]
	v_mfma_f32_16x16x32_f16 v[100:103], v[130:133], v[218:221], v[100:103]
	v_mfma_f32_16x16x32_f16 v[96:99], v[138:141], v[218:221], v[96:99]
	v_mfma_f32_16x16x32_f16 v[124:127], v[134:137], v[198:201], v[124:127]
	v_mfma_f32_16x16x32_f16 v[120:123], v[162:165], v[198:201], v[120:123]
	v_mfma_f32_16x16x32_f16 v[116:119], v[134:137], v[206:209], v[116:119]
	v_mfma_f32_16x16x32_f16 v[112:115], v[162:165], v[206:209], v[112:115]
	v_mfma_f32_16x16x32_f16 v[108:111], v[134:137], v[214:217], v[108:111]
	v_mfma_f32_16x16x32_f16 v[104:107], v[162:165], v[214:217], v[104:107]
	v_mfma_f32_16x16x32_f16 v[100:103], v[134:137], v[222:225], v[100:103]
	v_mfma_f32_16x16x32_f16 v[96:99], v[162:165], v[222:225], v[96:99]
	v_mfma_f32_16x16x32_f16 v[60:63], v[166:169], v[194:197], v[60:63]
	v_mfma_f32_16x16x32_f16 v[56:59], v[186:189], v[194:197], v[56:59]
	v_mfma_f32_16x16x32_f16 v[52:55], v[166:169], v[202:205], v[52:55]
	v_mfma_f32_16x16x32_f16 v[48:51], v[186:189], v[202:205], v[48:51]
	v_mfma_f32_16x16x32_f16 v[44:47], v[166:169], v[210:213], v[44:47]
	v_mfma_f32_16x16x32_f16 v[40:43], v[186:189], v[210:213], v[40:43]
	v_mfma_f32_16x16x32_f16 v[36:39], v[166:169], v[218:221], v[36:39]
	v_mfma_f32_16x16x32_f16 v[32:35], v[186:189], v[218:221], v[32:35]
	v_mfma_f32_16x16x32_f16 v[60:63], v[170:173], v[198:201], v[60:63]
	v_mfma_f32_16x16x32_f16 v[56:59], v[190:193], v[198:201], v[56:59]
	v_mfma_f32_16x16x32_f16 v[52:55], v[170:173], v[206:209], v[52:55]
	v_mfma_f32_16x16x32_f16 v[48:51], v[190:193], v[206:209], v[48:51]
	v_mfma_f32_16x16x32_f16 v[44:47], v[170:173], v[214:217], v[44:47]
	v_mfma_f32_16x16x32_f16 v[40:43], v[190:193], v[214:217], v[40:43]
	v_mfma_f32_16x16x32_f16 v[36:39], v[170:173], v[222:225], v[36:39]
	v_mfma_f32_16x16x32_f16 v[32:35], v[190:193], v[222:225], v[32:35]
	s_setprio 0
	s_barrier
	s_add_i32 s54, s68, s20
	s_mov_b32 m0, s54
	ds_read_b128 v[194:197], v240 offset:49152
	ds_read_b128 v[198:201], v240 offset:50176
	ds_read_b128 v[202:205], v240 offset:51200
	ds_read_b128 v[206:209], v240 offset:52224
	ds_read_b128 v[210:213], v240 offset:53248
	ds_read_b128 v[214:217], v240 offset:54272
	ds_read_b128 v[218:221], v240 offset:55296
	ds_read_b128 v[222:225], v240 offset:56320
	global_load_lds_dwordx4 v146, s[98:99]
	s_add_i32 m0, s54, 0x2000
	s_add_u32 s42, s42, 0x40080
	s_addc_u32 s43, s43, 0
	s_add_i32 s54, s69, s20
	global_load_lds_dwordx4 v142, s[98:99]
	s_mov_b32 m0, s54
	s_nop 0
	global_load_lds_dwordx4 v146, s[42:43]
	s_add_i32 m0, s54, 0x2000
	s_nop 0
	global_load_lds_dwordx4 v142, s[42:43]
	s_mov_b32 m0, s44
	s_nop 0
	global_load_lds_dwordx4 v148, s[100:101]
	s_mov_b32 m0, s45
	s_nop 0
	global_load_lds_dwordx4 v144, s[100:101]
	s_waitcnt vmcnt(8)
	s_waitcnt lgkmcnt(0)
	s_barrier
	s_setprio 1
	s_waitcnt lgkmcnt(0)
	v_mfma_f32_16x16x32_f16 v[92:95], v[130:133], v[194:197], v[92:95]
	v_mfma_f32_16x16x32_f16 v[88:91], v[138:141], v[194:197], v[88:91]
	v_mfma_f32_16x16x32_f16 v[84:87], v[130:133], v[202:205], v[84:87]
	v_mfma_f32_16x16x32_f16 v[80:83], v[138:141], v[202:205], v[80:83]
	v_mfma_f32_16x16x32_f16 v[76:79], v[130:133], v[210:213], v[76:79]
	v_mfma_f32_16x16x32_f16 v[72:75], v[138:141], v[210:213], v[72:75]
	v_mfma_f32_16x16x32_f16 v[68:71], v[130:133], v[218:221], v[68:71]
	v_mfma_f32_16x16x32_f16 v[64:67], v[138:141], v[218:221], v[64:67]
	v_mfma_f32_16x16x32_f16 v[92:95], v[134:137], v[198:201], v[92:95]
	v_mfma_f32_16x16x32_f16 v[88:91], v[162:165], v[198:201], v[88:91]
	v_mfma_f32_16x16x32_f16 v[84:87], v[134:137], v[206:209], v[84:87]
	v_mfma_f32_16x16x32_f16 v[80:83], v[162:165], v[206:209], v[80:83]
	v_mfma_f32_16x16x32_f16 v[76:79], v[134:137], v[214:217], v[76:79]
	v_mfma_f32_16x16x32_f16 v[72:75], v[162:165], v[214:217], v[72:75]
	v_mfma_f32_16x16x32_f16 v[68:71], v[134:137], v[222:225], v[68:71]
	v_mfma_f32_16x16x32_f16 v[64:67], v[162:165], v[222:225], v[64:67]
	v_mfma_f32_16x16x32_f16 v[28:31], v[166:169], v[194:197], v[28:31]
	v_mfma_f32_16x16x32_f16 v[24:27], v[186:189], v[194:197], v[24:27]
	v_mfma_f32_16x16x32_f16 v[20:23], v[166:169], v[202:205], v[20:23]
	v_mfma_f32_16x16x32_f16 v[16:19], v[186:189], v[202:205], v[16:19]
	v_mfma_f32_16x16x32_f16 v[12:15], v[166:169], v[210:213], v[12:15]
	v_mfma_f32_16x16x32_f16 v[8:11], v[186:189], v[210:213], v[8:11]
	v_mfma_f32_16x16x32_f16 v[4:7], v[166:169], v[218:221], v[4:7]
	v_mfma_f32_16x16x32_f16 v[0:3], v[186:189], v[218:221], v[0:3]
	v_mfma_f32_16x16x32_f16 v[28:31], v[170:173], v[198:201], v[28:31]
	v_mfma_f32_16x16x32_f16 v[24:27], v[190:193], v[198:201], v[24:27]
	v_mfma_f32_16x16x32_f16 v[20:23], v[170:173], v[206:209], v[20:23]
	v_mfma_f32_16x16x32_f16 v[16:19], v[190:193], v[206:209], v[16:19]
	v_mfma_f32_16x16x32_f16 v[12:15], v[170:173], v[214:217], v[12:15]
	v_mfma_f32_16x16x32_f16 v[8:11], v[190:193], v[214:217], v[8:11]
	v_mfma_f32_16x16x32_f16 v[4:7], v[170:173], v[222:225], v[4:7]
	v_mfma_f32_16x16x32_f16 v[0:3], v[190:193], v[222:225], v[0:3]
	s_setprio 0
	s_barrier
	s_add_i32 s67, s67, 2
	s_add_u32 s0, s0, 0x100
	s_addc_u32 s1, s1, 0
	s_add_u32 s59, s59, 0x100
	s_addc_u32 s61, s61, 0
	s_cmp_gt_u32 s67, 13
	s_cbranch_scc0 .LBB0_256
	s_and_b64 vcc, exec, s[8:9]
	s_cbranch_vccz .LBB0_259
	s_barrier

; #define PG8_STAGE(bufoff, gbase, voff) do { _Pragma("unroll") for (int _i = 0; _i < 2; ++_i) \
;         __builtin_amdgcn_global_load_lds((const unsigned*)((const char*)(gbase) + (voff)[_i]), (PG8_LAS unsigned*)(lds + (bufoff) + ldsw + _i * 8192), 16, 0, 0); } while (0)
; #define PG8_LDA(dst, b, h) do { _Pragma("unroll") for (int m = 0; m < 4; ++m) _Pragma("unroll") for (int k = 0; k < 2; ++k) dst[m][k] = *(const PG8_LAS bf16x8*)(lds + PG8_SA(b, h) + aoff + m * 2048 + k * 1024); } while (0)
; #define PG8_LDB(dst, b, h) do { _Pragma("unroll") for (int n = 0; n < 2; ++n) _Pragma("unroll") for (int k = 0; k < 2; ++k) dst[n][k] = *(const PG8_LAS bf16x8*)(lds + PG8_SB(b, h) + boff + n * 2048 + k * 1024); } while (0)
; #define PG8_MMA(ai, bj, At, Bt) do { __builtin_amdgcn_s_setprio(1); _Pragma("unroll") for (int m = 0; m < 4; ++m) _Pragma("unroll") for (int n = 0; n < 2; ++n) _Pragma("unroll") for (int k = 0; k < 2; ++k) \
;         acc[ai][bj][m][n] = mma16<F16>(Bt[n][k], At[m][k], acc[ai][bj][m][n]); __builtin_amdgcn_s_setprio(0); } while (0)
; #define PG8_WAIT_V(n) asm volatile("s_waitcnt vmcnt(" #n ")" ::: "memory")
; #define PG8_WAIT_L(n) asm volatile("s_waitcnt lgkmcnt(" #n ")" ::: "memory")
; #define PG8_BAR __builtin_amdgcn_s_barrier()
; #define PG8_SCHED __builtin_amdgcn_sched_barrier(0)
; template <class Epi, class Sched, bool ALIGN_EPI = false, bool SP2 = false, bool F16 = false>
; __device__ __forceinline__ void gemm_phase(PG8_LAS unsigned char* lds, const Gemm g, const Sched& S, const Epi& E) {
;     ...
;             PG8_LDB(B0, 0, 0); PG8_LDB(B1, 0, 1); PG8_SCHED; PG8_LDA(At, 0, 0); PG8_STAGE(PG8_SA(1, 1), a1 + hstep, voffA);
;             PG8_WAIT_V(8); PG8_WAIT_L(0); PG8_BAR; PG8_MMA(0, 0, At, B0); PG8_MMA(0, 1, At, B1); PG8_BAR; PG8_SCHED;
;             PG8_LDA(At, 0, 1); PG8_STAGE(PG8_SB(0, 0), b2, voffB); PG8_STAGE(PG8_SB(0, 1), b2 + hstep, voffB); PG8_STAGE(PG8_SA(0, 0), a2, voffA);
;             PG8_WAIT_V(8); PG8_WAIT_L(0); PG8_BAR; PG8_MMA(1, 0, At, B0); PG8_MMA(1, 1, At, B1); PG8_BAR; PG8_SCHED;
;             PG8_LDB(B0, 1, 0); PG8_LDB(B1, 1, 1); PG8_SCHED; PG8_LDA(At, 1, 0); PG8_STAGE(PG8_SA(0, 1), a2 + hstep, voffA);
.LBB0_801:
	s_add_u32 s0, s60, s62
	s_addc_u32 s1, s61, s63
	s_add_u32 s0, s0, 0x100
	s_addc_u32 s1, s1, 0
	s_add_u32 s4, s74, s62
	s_addc_u32 s5, s75, s63
	s_add_i32 s6, 0, 0x10000
	s_cmpk_eq_i32 s62, 0x700
	s_cselect_b32 s65, s55, s1
	s_cselect_b32 s64, s70, s0
	v_add_u32_e32 v128, s6, v239
	s_cselect_b32 s1, s53, s5
	s_cselect_b32 s0, s71, s4
	s_add_i32 s7, 0, 0x14000
	ds_read_b128 v[136:139], v128
	ds_read_b128 v[140:143], v128 offset:1024
	ds_read_b128 v[144:147], v128 offset:2048
	ds_read_b128 v[148:151], v128 offset:3072
	v_add_u32_e32 v128, s7, v239
	ds_read_b128 v[152:155], v128
	ds_read_b128 v[156:159], v128 offset:1024
	ds_read_b128 v[190:193], v128 offset:2048
	ds_read_b128 v[194:197], v128 offset:3072
	v_lshl_add_u64 v[130:131], v[132:133], 0, s[62:63]
	s_add_i32 m0, s11, 0xc000
	ds_read_b128 v[198:201], v240
	ds_read_b128 v[202:205], v240 offset:1024
	ds_read_b128 v[206:209], v240 offset:2048
	ds_read_b128 v[210:213], v240 offset:3072
	ds_read_b128 v[214:217], v240 offset:4096
	ds_read_b128 v[218:221], v240 offset:5120
	ds_read_b128 v[222:225], v240 offset:6144
	ds_read_b128 v[242:245], v240 offset:7168
	global_load_lds_dwordx4 v[130:131], off
	v_lshl_add_u64 v[130:131], v[134:135], 0, s[62:63]
	s_add_i32 m0, s11, 0xe000
	s_nop 0
	global_load_lds_dwordx4 v[130:131], off
	s_waitcnt vmcnt(8)
	s_waitcnt lgkmcnt(0)
	s_barrier
	s_setprio 1
	s_waitcnt lgkmcnt(0)
	v_mfma_f32_16x16x32_bf16 v[124:127], v[136:139], v[198:201], v[124:127]
	v_mfma_f32_16x16x32_bf16 v[120:123], v[144:147], v[198:201], v[120:123]
	v_mfma_f32_16x16x32_bf16 v[116:119], v[136:139], v[206:209], v[116:119]
	v_mfma_f32_16x16x32_bf16 v[112:115], v[144:147], v[206:209], v[112:115]
	v_mfma_f32_16x16x32_bf16 v[108:111], v[136:139], v[214:217], v[108:111]
	v_mfma_f32_16x16x32_bf16 v[104:107], v[144:147], v[214:217], v[104:107]
	v_mfma_f32_16x16x32_bf16 v[100:103], v[136:139], v[222:225], v[100:103]
	v_mfma_f32_16x16x32_bf16 v[96:99], v[144:147], v[222:225], v[96:99]
	v_mfma_f32_16x16x32_bf16 v[124:127], v[140:143], v[202:205], v[124:127]
	v_mfma_f32_16x16x32_bf16 v[120:123], v[148:151], v[202:205], v[120:123]
	v_mfma_f32_16x16x32_bf16 v[116:119], v[140:143], v[210:213], v[116:119]
	v_mfma_f32_16x16x32_bf16 v[112:115], v[148:151], v[210:213], v[112:115]
	v_mfma_f32_16x16x32_bf16 v[108:111], v[140:143], v[218:221], v[108:111]
	v_mfma_f32_16x16x32_bf16 v[104:107], v[148:151], v[218:221], v[104:107]
	v_mfma_f32_16x16x32_bf16 v[100:103], v[140:143], v[242:245], v[100:103]
	v_mfma_f32_16x16x32_bf16 v[96:99], v[148:151], v[242:245], v[96:99]
	v_mfma_f32_16x16x32_bf16 v[60:63], v[152:155], v[198:201], v[60:63]
	v_mfma_f32_16x16x32_bf16 v[56:59], v[190:193], v[198:201], v[56:59]
	v_mfma_f32_16x16x32_bf16 v[52:55], v[152:155], v[206:209], v[52:55]
	v_mfma_f32_16x16x32_bf16 v[48:51], v[190:193], v[206:209], v[48:51]
	v_mfma_f32_16x16x32_bf16 v[44:47], v[152:155], v[214:217], v[44:47]
	v_mfma_f32_16x16x32_bf16 v[40:43], v[190:193], v[214:217], v[40:43]
	v_mfma_f32_16x16x32_bf16 v[36:39], v[152:155], v[222:225], v[36:39]
	v_mfma_f32_16x16x32_bf16 v[32:35], v[190:193], v[222:225], v[32:35]
	v_mfma_f32_16x16x32_bf16 v[60:63], v[156:159], v[202:205], v[60:63]
	v_mfma_f32_16x16x32_bf16 v[56:59], v[194:197], v[202:205], v[56:59]
	v_mfma_f32_16x16x32_bf16 v[52:55], v[156:159], v[210:213], v[52:55]
	v_mfma_f32_16x16x32_bf16 v[48:51], v[194:197], v[210:213], v[48:51]
	v_mfma_f32_16x16x32_bf16 v[44:47], v[156:159], v[218:221], v[44:47]
	v_mfma_f32_16x16x32_bf16 v[40:43], v[194:197], v[218:221], v[40:43]
	v_mfma_f32_16x16x32_bf16 v[36:39], v[156:159], v[242:245], v[36:39]
	v_mfma_f32_16x16x32_bf16 v[32:35], v[194:197], v[242:245], v[32:35]
	s_setprio 0
	s_barrier
	s_add_i32 s4, s6, s10
	v_lshl_add_u64 v[130:131], s[0:1], 0, v[166:167]
	s_mov_b32 m0, s4
	ds_read_b128 v[198:201], v240 offset:16384
	ds_read_b128 v[202:205], v240 offset:17408
	ds_read_b128 v[206:209], v240 offset:18432
	ds_read_b128 v[210:213], v240 offset:19456
	ds_read_b128 v[214:217], v240 offset:20480
	ds_read_b128 v[218:221], v240 offset:21504
	ds_read_b128 v[222:225], v240 offset:22528
	ds_read_b128 v[242:245], v240 offset:23552
	global_load_lds_dwordx4 v[130:131], off
	s_add_i32 m0, s4, 0x2000
	s_add_u32 s4, s0, 0x40000
	v_lshl_add_u64 v[160:161], s[0:1], 0, v[162:163]
	s_addc_u32 s5, s1, 0
	s_add_i32 s6, s7, s10
	global_load_lds_dwordx4 v[160:161], off
	v_lshl_add_u64 v[246:247], s[4:5], 0, v[166:167]
	s_mov_b32 m0, s6
	v_lshl_add_u64 v[248:249], s[64:65], 0, v[164:165]
	global_load_lds_dwordx4 v[246:247], off
	v_lshl_add_u64 v[246:247], s[4:5], 0, v[162:163]
	s_add_i32 m0, s6, 0x2000
	s_nop 0
	global_load_lds_dwordx4 v[246:247], off
	v_lshl_add_u64 v[246:247], s[64:65], 0, v[168:169]
	s_mov_b32 m0, s11
	s_nop 0
	global_load_lds_dwordx4 v[246:247], off
	s_mov_b32 m0, s13
	s_nop 0
	global_load_lds_dwordx4 v[248:249], off
	s_waitcnt vmcnt(8)
	s_waitcnt lgkmcnt(0)
	s_barrier
; #define PG8_STAGE(bufoff, gbase, voff) do { _Pragma("unroll") for (int _i = 0; _i < 2; ++_i) \
;         __builtin_amdgcn_global_load_lds((const unsigned*)((const char*)(gbase) + (voff)[_i]), (PG8_LAS unsigned*)(lds + (bufoff) + ldsw + _i * 8192), 16, 0, 0); } while (0)
; #define PG8_LDA(dst, b, h) do { _Pragma("unroll") for (int m = 0; m < 4; ++m) _Pragma("unroll") for (int k = 0; k < 2; ++k) dst[m][k] = *(const PG8_LAS bf16x8*)(lds + PG8_SA(b, h) + aoff + m * 2048 + k * 1024); } while (0)
; #define PG8_MMA(ai, bj, At, Bt) do { __builtin_amdgcn_s_setprio(1); _Pragma("unroll") for (int m = 0; m < 4; ++m) _Pragma("unroll") for (int n = 0; n < 2; ++n) _Pragma("unroll") for (int k = 0; k < 2; ++k) \
;         acc[ai][bj][m][n] = mma16<F16>(Bt[n][k], At[m][k], acc[ai][bj][m][n]); __builtin_amdgcn_s_setprio(0); } while (0)
; #define PG8_WAIT_V(n) asm volatile("s_waitcnt vmcnt(" #n ")" ::: "memory")
; #define PG8_WAIT_L(n) asm volatile("s_waitcnt lgkmcnt(" #n ")" ::: "memory")
; #define PG8_BAR __builtin_amdgcn_s_barrier()
; #define PG8_SCHED __builtin_amdgcn_sched_barrier(0)
; template <class Epi, class Sched, bool ALIGN_EPI = false, bool SP2 = false, bool F16 = false>
; __device__ __forceinline__ void gemm_phase(PG8_LAS unsigned char* lds, const Gemm g, const Sched& S, const Epi& E) {
;     ...
;             PG8_WAIT_V(8); PG8_WAIT_L(0); PG8_BAR; PG8_MMA(0, 0, At, B0); PG8_MMA(0, 1, At, B1); PG8_BAR; PG8_SCHED;
;             PG8_LDA(At, 1, 1); PG8_STAGE(PG8_SB(1, 0), b3, voffB); PG8_STAGE(PG8_SB(1, 1), b3 + hstep, voffB); PG8_STAGE(PG8_SA(1, 0), a3, voffA);
	s_setprio 1
	s_waitcnt lgkmcnt(0)
	v_mfma_f32_16x16x32_bf16 v[92:95], v[136:139], v[198:201], v[92:95]
	v_mfma_f32_16x16x32_bf16 v[88:91], v[144:147], v[198:201], v[88:91]
	v_mfma_f32_16x16x32_bf16 v[84:87], v[136:139], v[206:209], v[84:87]
	v_mfma_f32_16x16x32_bf16 v[80:83], v[144:147], v[206:209], v[80:83]
	v_mfma_f32_16x16x32_bf16 v[76:79], v[136:139], v[214:217], v[76:79]
	v_mfma_f32_16x16x32_bf16 v[72:75], v[144:147], v[214:217], v[72:75]
	v_mfma_f32_16x16x32_bf16 v[68:71], v[136:139], v[222:225], v[68:71]
	v_mfma_f32_16x16x32_bf16 v[64:67], v[144:147], v[222:225], v[64:67]
	v_mfma_f32_16x16x32_bf16 v[92:95], v[140:143], v[202:205], v[92:95]
	v_mfma_f32_16x16x32_bf16 v[88:91], v[148:151], v[202:205], v[88:91]
	v_mfma_f32_16x16x32_bf16 v[84:87], v[140:143], v[210:213], v[84:87]
	v_mfma_f32_16x16x32_bf16 v[80:83], v[148:151], v[210:213], v[80:83]
	v_mfma_f32_16x16x32_bf16 v[76:79], v[140:143], v[218:221], v[76:79]
	v_mfma_f32_16x16x32_bf16 v[72:75], v[148:151], v[218:221], v[72:75]
	v_mfma_f32_16x16x32_bf16 v[68:71], v[140:143], v[242:245], v[68:71]
	v_mfma_f32_16x16x32_bf16 v[64:67], v[148:151], v[242:245], v[64:67]
	v_mfma_f32_16x16x32_bf16 v[28:31], v[152:155], v[198:201], v[28:31]
	v_mfma_f32_16x16x32_bf16 v[24:27], v[190:193], v[198:201], v[24:27]
	v_mfma_f32_16x16x32_bf16 v[20:23], v[152:155], v[206:209], v[20:23]
	v_mfma_f32_16x16x32_bf16 v[16:19], v[190:193], v[206:209], v[16:19]
	v_mfma_f32_16x16x32_bf16 v[12:15], v[152:155], v[214:217], v[12:15]
	v_mfma_f32_16x16x32_bf16 v[8:11], v[190:193], v[214:217], v[8:11]
	v_mfma_f32_16x16x32_bf16 v[4:7], v[152:155], v[222:225], v[4:7]
	v_mfma_f32_16x16x32_bf16 v[0:3], v[190:193], v[222:225], v[0:3]
	v_mfma_f32_16x16x32_bf16 v[28:31], v[156:159], v[202:205], v[28:31]
	v_mfma_f32_16x16x32_bf16 v[24:27], v[194:197], v[202:205], v[24:27]
	v_mfma_f32_16x16x32_bf16 v[20:23], v[156:159], v[210:213], v[20:23]
	v_mfma_f32_16x16x32_bf16 v[16:19], v[194:197], v[210:213], v[16:19]
	v_mfma_f32_16x16x32_bf16 v[12:15], v[156:159], v[218:221], v[12:15]
	v_mfma_f32_16x16x32_bf16 v[8:11], v[194:197], v[218:221], v[8:11]
	v_mfma_f32_16x16x32_bf16 v[4:7], v[156:159], v[242:245], v[4:7]
	v_mfma_f32_16x16x32_bf16 v[0:3], v[194:197], v[242:245], v[0:3]
	s_setprio 0
	s_barrier
	s_add_i32 s6, 0, 0x18000
	v_add_u32_e32 v128, s6, v239
	s_add_i32 s7, 0, 0x1c000
	ds_read_b128 v[136:139], v128
	ds_read_b128 v[140:143], v128 offset:1024
	ds_read_b128 v[144:147], v128 offset:2048
	ds_read_b128 v[148:151], v128 offset:3072
	v_add_u32_e32 v128, s7, v239
	ds_read_b128 v[152:155], v128
	ds_read_b128 v[156:159], v128 offset:1024
	ds_read_b128 v[190:193], v128 offset:2048
	ds_read_b128 v[194:197], v128 offset:3072
	s_add_u32 s4, s64, 0x40000
	s_addc_u32 s5, s65, 0
	s_mov_b32 m0, s14
	v_lshl_add_u64 v[250:251], s[4:5], 0, v[168:169]
	ds_read_b128 v[198:201], v240 offset:32768
	ds_read_b128 v[202:205], v240 offset:33792
	ds_read_b128 v[206:209], v240 offset:34816
	ds_read_b128 v[210:213], v240 offset:35840
	ds_read_b128 v[214:217], v240 offset:36864
	ds_read_b128 v[218:221], v240 offset:37888
	ds_read_b128 v[222:225], v240 offset:38912
	ds_read_b128 v[242:245], v240 offset:39936
	global_load_lds_dwordx4 v[250:251], off
	v_lshl_add_u64 v[250:251], s[4:5], 0, v[164:165]
	s_mov_b32 m0, s15
	s_nop 0
	global_load_lds_dwordx4 v[250:251], off
	s_waitcnt vmcnt(8)
	s_waitcnt lgkmcnt(0)
	s_barrier
	s_setprio 1
	s_waitcnt lgkmcnt(0)
	v_mfma_f32_16x16x32_bf16 v[124:127], v[136:139], v[198:201], v[124:127]
	v_mfma_f32_16x16x32_bf16 v[120:123], v[144:147], v[198:201], v[120:123]
	v_mfma_f32_16x16x32_bf16 v[116:119], v[136:139], v[206:209], v[116:119]
	v_mfma_f32_16x16x32_bf16 v[112:115], v[144:147], v[206:209], v[112:115]
	v_mfma_f32_16x16x32_bf16 v[108:111], v[136:139], v[214:217], v[108:111]
	v_mfma_f32_16x16x32_bf16 v[104:107], v[144:147], v[214:217], v[104:107]
	v_mfma_f32_16x16x32_bf16 v[100:103], v[136:139], v[222:225], v[100:103]
	v_mfma_f32_16x16x32_bf16 v[96:99], v[144:147], v[222:225], v[96:99]
	v_mfma_f32_16x16x32_bf16 v[124:127], v[140:143], v[202:205], v[124:127]
	v_mfma_f32_16x16x32_bf16 v[120:123], v[148:151], v[202:205], v[120:123]
	v_mfma_f32_16x16x32_bf16 v[116:119], v[140:143], v[210:213], v[116:119]
	v_mfma_f32_16x16x32_bf16 v[112:115], v[148:151], v[210:213], v[112:115]
	v_mfma_f32_16x16x32_bf16 v[108:111], v[140:143], v[218:221], v[108:111]
	v_mfma_f32_16x16x32_bf16 v[104:107], v[148:151], v[218:221], v[104:107]
	v_mfma_f32_16x16x32_bf16 v[100:103], v[140:143], v[242:245], v[100:103]
	v_mfma_f32_16x16x32_bf16 v[96:99], v[148:151], v[242:245], v[96:99]
	v_mfma_f32_16x16x32_bf16 v[60:63], v[152:155], v[198:201], v[60:63]
	v_mfma_f32_16x16x32_bf16 v[56:59], v[190:193], v[198:201], v[56:59]
	v_mfma_f32_16x16x32_bf16 v[52:55], v[152:155], v[206:209], v[52:55]
	v_mfma_f32_16x16x32_bf16 v[48:51], v[190:193], v[206:209], v[48:51]
	v_mfma_f32_16x16x32_bf16 v[44:47], v[152:155], v[214:217], v[44:47]
	v_mfma_f32_16x16x32_bf16 v[40:43], v[190:193], v[214:217], v[40:43]
	v_mfma_f32_16x16x32_bf16 v[36:39], v[152:155], v[222:225], v[36:39]
	v_mfma_f32_16x16x32_bf16 v[32:35], v[190:193], v[222:225], v[32:35]
	v_mfma_f32_16x16x32_bf16 v[60:63], v[156:159], v[202:205], v[60:63]
	v_mfma_f32_16x16x32_bf16 v[56:59], v[194:197], v[202:205], v[56:59]
	v_mfma_f32_16x16x32_bf16 v[52:55], v[156:159], v[210:213], v[52:55]
	v_mfma_f32_16x16x32_bf16 v[48:51], v[194:197], v[210:213], v[48:51]
	v_mfma_f32_16x16x32_bf16 v[44:47], v[156:159], v[218:221], v[44:47]
	v_mfma_f32_16x16x32_bf16 v[40:43], v[194:197], v[218:221], v[40:43]
	v_mfma_f32_16x16x32_bf16 v[36:39], v[156:159], v[242:245], v[36:39]
	v_mfma_f32_16x16x32_bf16 v[32:35], v[194:197], v[242:245], v[32:35]
	s_setprio 0
	s_barrier
; #define PG8_STAGE(bufoff, gbase, voff) do { _Pragma("unroll") for (int _i = 0; _i < 2; ++_i) \
;         __builtin_amdgcn_global_load_lds((const unsigned*)((const char*)(gbase) + (voff)[_i]), (PG8_LAS unsigned*)(lds + (bufoff) + ldsw + _i * 8192), 16, 0, 0); } while (0)
; #define PG8_LDA(dst, b, h) do { _Pragma("unroll") for (int m = 0; m < 4; ++m) _Pragma("unroll") for (int k = 0; k < 2; ++k) dst[m][k] = *(const PG8_LAS bf16x8*)(lds + PG8_SA(b, h) + aoff + m * 2048 + k * 1024); } while (0)
; #define PG8_MMA(ai, bj, At, Bt) do { __builtin_amdgcn_s_setprio(1); _Pragma("unroll") for (int m = 0; m < 4; ++m) _Pragma("unroll") for (int n = 0; n < 2; ++n) _Pragma("unroll") for (int k = 0; k < 2; ++k) \
;         acc[ai][bj][m][n] = mma16<F16>(Bt[n][k], At[m][k], acc[ai][bj][m][n]); __builtin_amdgcn_s_setprio(0); } while (0)
; #define PG8_WAIT_V(n) asm volatile("s_waitcnt vmcnt(" #n ")" ::: "memory")
; #define PG8_WAIT_L(n) asm volatile("s_waitcnt lgkmcnt(" #n ")" ::: "memory")
; #define PG8_BAR __builtin_amdgcn_s_barrier()
; #define PG8_SCHED __builtin_amdgcn_sched_barrier(0)
; template <class Epi, class Sched, bool ALIGN_EPI = false, bool SP2 = false, bool F16 = false>
; __device__ __forceinline__ void gemm_phase(PG8_LAS unsigned char* lds, const Gemm g, const Sched& S, const Epi& E) {
;     ...
;         for (int t = 0; t < nt; t += 2) {
;             if constexpr (Epi::KHOOK) { if (t == 4 || t == 10) E.khook(acc, cur, t, wr, fr); }
;     ...
;             PG8_LDA(At, 1, 1); PG8_STAGE(PG8_SB(1, 0), b3, voffB); PG8_STAGE(PG8_SB(1, 1), b3 + hstep, voffB); PG8_STAGE(PG8_SA(1, 0), a3, voffA);
;             PG8_WAIT_V(8); PG8_WAIT_L(0); PG8_BAR; PG8_MMA(1, 0, At, B0); PG8_MMA(1, 1, At, B1); PG8_BAR; PG8_SCHED;
	s_add_i32 s4, s6, s10
	v_lshl_add_u64 v[130:131], v[130:131], 0, s[16:17]
	s_mov_b32 m0, s4
	ds_read_b128 v[198:201], v240 offset:49152
	ds_read_b128 v[202:205], v240 offset:50176
	ds_read_b128 v[206:209], v240 offset:51200
	ds_read_b128 v[210:213], v240 offset:52224
	ds_read_b128 v[214:217], v240 offset:53248
	ds_read_b128 v[218:221], v240 offset:54272
	ds_read_b128 v[222:225], v240 offset:55296
	ds_read_b128 v[242:245], v240 offset:56320
	global_load_lds_dwordx4 v[130:131], off
	s_add_i32 m0, s4, 0x2000
	s_add_u32 s0, s0, 0x40080
	v_lshl_add_u64 v[130:131], v[160:161], 0, s[16:17]
	s_addc_u32 s1, s1, 0
	s_add_i32 s4, s7, s10
	global_load_lds_dwordx4 v[130:131], off
	v_lshl_add_u64 v[130:131], s[0:1], 0, v[166:167]
	s_mov_b32 m0, s4
	s_nop 0
	global_load_lds_dwordx4 v[130:131], off
	v_lshl_add_u64 v[130:131], s[0:1], 0, v[162:163]
	s_add_i32 m0, s4, 0x2000
	s_nop 0
	global_load_lds_dwordx4 v[130:131], off
	v_lshl_add_u64 v[130:131], v[246:247], 0, s[16:17]
	s_mov_b32 m0, s30
	s_nop 0
	global_load_lds_dwordx4 v[130:131], off
	v_lshl_add_u64 v[130:131], v[248:249], 0, s[16:17]
	s_mov_b32 m0, s31
	s_nop 0
	global_load_lds_dwordx4 v[130:131], off
	s_waitcnt vmcnt(8)
	s_waitcnt lgkmcnt(0)
	s_barrier
	s_setprio 1
	s_waitcnt lgkmcnt(0)
	v_mfma_f32_16x16x32_bf16 v[92:95], v[136:139], v[198:201], v[92:95]
	v_mfma_f32_16x16x32_bf16 v[88:91], v[144:147], v[198:201], v[88:91]
	v_mfma_f32_16x16x32_bf16 v[84:87], v[136:139], v[206:209], v[84:87]
	v_mfma_f32_16x16x32_bf16 v[80:83], v[144:147], v[206:209], v[80:83]
	v_mfma_f32_16x16x32_bf16 v[76:79], v[136:139], v[214:217], v[76:79]
	v_mfma_f32_16x16x32_bf16 v[72:75], v[144:147], v[214:217], v[72:75]
	v_mfma_f32_16x16x32_bf16 v[68:71], v[136:139], v[222:225], v[68:71]
	v_mfma_f32_16x16x32_bf16 v[64:67], v[144:147], v[222:225], v[64:67]
	v_mfma_f32_16x16x32_bf16 v[92:95], v[140:143], v[202:205], v[92:95]
	v_mfma_f32_16x16x32_bf16 v[88:91], v[148:151], v[202:205], v[88:91]
	v_mfma_f32_16x16x32_bf16 v[84:87], v[140:143], v[210:213], v[84:87]
	v_mfma_f32_16x16x32_bf16 v[80:83], v[148:151], v[210:213], v[80:83]
	v_mfma_f32_16x16x32_bf16 v[76:79], v[140:143], v[218:221], v[76:79]
	v_mfma_f32_16x16x32_bf16 v[72:75], v[148:151], v[218:221], v[72:75]
	v_mfma_f32_16x16x32_bf16 v[68:71], v[140:143], v[242:245], v[68:71]
	v_mfma_f32_16x16x32_bf16 v[64:67], v[148:151], v[242:245], v[64:67]
	v_mfma_f32_16x16x32_bf16 v[28:31], v[152:155], v[198:201], v[28:31]
	v_mfma_f32_16x16x32_bf16 v[24:27], v[190:193], v[198:201], v[24:27]
	v_mfma_f32_16x16x32_bf16 v[20:23], v[152:155], v[206:209], v[20:23]
	v_mfma_f32_16x16x32_bf16 v[16:19], v[190:193], v[206:209], v[16:19]
	v_mfma_f32_16x16x32_bf16 v[12:15], v[152:155], v[214:217], v[12:15]
	v_mfma_f32_16x16x32_bf16 v[8:11], v[190:193], v[214:217], v[8:11]
	v_mfma_f32_16x16x32_bf16 v[4:7], v[152:155], v[222:225], v[4:7]
	v_mfma_f32_16x16x32_bf16 v[0:3], v[190:193], v[222:225], v[0:3]
	v_mfma_f32_16x16x32_bf16 v[28:31], v[156:159], v[202:205], v[28:31]
	v_mfma_f32_16x16x32_bf16 v[24:27], v[194:197], v[202:205], v[24:27]
	v_mfma_f32_16x16x32_bf16 v[20:23], v[156:159], v[210:213], v[20:23]
	v_mfma_f32_16x16x32_bf16 v[16:19], v[194:197], v[210:213], v[16:19]
	v_mfma_f32_16x16x32_bf16 v[12:15], v[156:159], v[218:221], v[12:15]
	v_mfma_f32_16x16x32_bf16 v[8:11], v[194:197], v[218:221], v[8:11]
	v_mfma_f32_16x16x32_bf16 v[4:7], v[156:159], v[242:245], v[4:7]
	v_mfma_f32_16x16x32_bf16 v[0:3], v[194:197], v[242:245], v[0:3]
	s_setprio 0
	s_barrier
	s_add_i32 s0, s78, 2
	s_add_u32 s62, s62, 0x100
	s_addc_u32 s63, s63, 0
	s_cmp_gt_u32 s78, 13
	s_cbranch_scc1 .LBB0_804
	s_mov_b32 s78, s0
	s_cmp_lt_i32 s78, 10
	s_cbranch_scc1 .LBB0_796
	s_branch .LBB0_795

; #define PG8_STAGE(bufoff, gbase, voff) do { _Pragma("unroll") for (int _i = 0; _i < 2; ++_i) \
;         __builtin_amdgcn_global_load_lds((const unsigned*)((const char*)(gbase) + (voff)[_i]), (PG8_LAS unsigned*)(lds + (bufoff) + ldsw + _i * 8192), 16, 0, 0); } while (0)
; #define PG8_LDA(dst, b, h) do { _Pragma("unroll") for (int m = 0; m < 4; ++m) _Pragma("unroll") for (int k = 0; k < 2; ++k) dst[m][k] = *(const PG8_LAS bf16x8*)(lds + PG8_SA(b, h) + aoff + m * 2048 + k * 1024); } while (0)
; #define PG8_LDB(dst, b, h) do { _Pragma("unroll") for (int n = 0; n < 2; ++n) _Pragma("unroll") for (int k = 0; k < 2; ++k) dst[n][k] = *(const PG8_LAS bf16x8*)(lds + PG8_SB(b, h) + boff + n * 2048 + k * 1024); } while (0)
; #define PG8_MMA(ai, bj, At, Bt) do { __builtin_amdgcn_s_setprio(1); _Pragma("unroll") for (int m = 0; m < 4; ++m) _Pragma("unroll") for (int n = 0; n < 2; ++n) _Pragma("unroll") for (int k = 0; k < 2; ++k) \
;         acc[ai][bj][m][n] = mma16<F16>(Bt[n][k], At[m][k], acc[ai][bj][m][n]); __builtin_amdgcn_s_setprio(0); } while (0)
; #define PG8_WAIT_V(n) asm volatile("s_waitcnt vmcnt(" #n ")" ::: "memory")
; #define PG8_WAIT_L(n) asm volatile("s_waitcnt lgkmcnt(" #n ")" ::: "memory")
; #define PG8_BAR __builtin_amdgcn_s_barrier()
; #define PG8_SCHED __builtin_amdgcn_sched_barrier(0)
; template <class Epi, class Sched, bool ALIGN_EPI = false, bool SP2 = false, bool F16 = false>
; __device__ __forceinline__ void gemm_phase(PG8_LAS unsigned char* lds, const Gemm g, const Sched& S, const Epi& E) {
;     ...
;             PG8_LDB(B0, 0, 0); PG8_LDB(B1, 0, 1); PG8_SCHED; PG8_LDA(At, 0, 0); PG8_STAGE(PG8_SA(1, 1), a1 + hstep, voffA);
;             PG8_WAIT_V(8); PG8_WAIT_L(0); PG8_BAR; PG8_MMA(0, 0, At, B0); PG8_MMA(0, 1, At, B1); PG8_BAR; PG8_SCHED;
;             PG8_LDA(At, 0, 1); PG8_STAGE(PG8_SB(0, 0), b2, voffB); PG8_STAGE(PG8_SB(0, 1), b2 + hstep, voffB); PG8_STAGE(PG8_SA(0, 0), a2, voffA);
;             PG8_WAIT_V(8); PG8_WAIT_L(0); PG8_BAR; PG8_MMA(1, 0, At, B0); PG8_MMA(1, 1, At, B1); PG8_BAR; PG8_SCHED;
.LBB0_904:
	s_add_u32 s56, s54, 0xfffc0080
	s_addc_u32 s57, s55, -1
	s_add_i32 s62, 0, 0x10000
	s_cmp_eq_u32 s61, 12
	s_cselect_b32 s59, s4, s57
	s_cselect_b32 s58, s5, s56
	s_cselect_b32 s57, s37, s60
	s_cselect_b32 s56, s47, s49
	s_add_i32 s64, 0, 0x14000
	ds_read_b128 v[32:35], v172
	ds_read_b128 v[36:39], v172 offset:1024
	ds_read_b128 v[40:43], v172 offset:2048
	ds_read_b128 v[44:47], v172 offset:3072
	ds_read_b128 v[156:159], v172 offset:16384
	ds_read_b128 v[168:171], v172 offset:17408
	ds_read_b128 v[186:189], v172 offset:18432
	ds_read_b128 v[190:193], v172 offset:19456
	s_add_i32 m0, s9, 0xc000
	ds_read_b128 v[194:197], v165
	ds_read_b128 v[198:201], v165 offset:1024
	ds_read_b128 v[202:205], v165 offset:2048
	ds_read_b128 v[206:209], v165 offset:3072
	ds_read_b128 v[210:213], v165 offset:4096
	ds_read_b128 v[214:217], v165 offset:5120
	ds_read_b128 v[218:221], v165 offset:6144
	ds_read_b128 v[222:225], v165 offset:7168
	global_load_lds_dwordx4 v152, s[54:55]
	s_add_i32 m0, s9, 0xe000
	s_nop 0
	global_load_lds_dwordx4 v154, s[54:55]
	s_waitcnt vmcnt(8)
	s_waitcnt lgkmcnt(0)
	s_barrier
	s_setprio 1
	s_waitcnt lgkmcnt(0)
	v_mfma_f32_16x16x32_f16 v[142:145], v[32:35], v[194:197], v[142:145]
	v_mfma_f32_16x16x32_f16 v[138:141], v[40:43], v[194:197], v[138:141]
	v_mfma_f32_16x16x32_f16 v[124:127], v[32:35], v[202:205], v[124:127]
	v_mfma_f32_16x16x32_f16 v[120:123], v[40:43], v[202:205], v[120:123]
	v_mfma_f32_16x16x32_f16 v[108:111], v[32:35], v[210:213], v[108:111]
	v_mfma_f32_16x16x32_f16 v[104:107], v[40:43], v[210:213], v[104:107]
	v_mfma_f32_16x16x32_f16 v[92:95], v[32:35], v[218:221], v[92:95]
	v_mfma_f32_16x16x32_f16 v[88:91], v[40:43], v[218:221], v[88:91]
	v_mfma_f32_16x16x32_f16 v[142:145], v[36:39], v[198:201], v[142:145]
	v_mfma_f32_16x16x32_f16 v[138:141], v[44:47], v[198:201], v[138:141]
	v_mfma_f32_16x16x32_f16 v[124:127], v[36:39], v[206:209], v[124:127]
	v_mfma_f32_16x16x32_f16 v[120:123], v[44:47], v[206:209], v[120:123]
	v_mfma_f32_16x16x32_f16 v[108:111], v[36:39], v[214:217], v[108:111]
	v_mfma_f32_16x16x32_f16 v[104:107], v[44:47], v[214:217], v[104:107]
	v_mfma_f32_16x16x32_f16 v[92:95], v[36:39], v[222:225], v[92:95]
	v_mfma_f32_16x16x32_f16 v[88:91], v[44:47], v[222:225], v[88:91]
	v_mfma_f32_16x16x32_f16 v[134:137], v[156:159], v[194:197], v[134:137]
	v_mfma_f32_16x16x32_f16 v[130:133], v[186:189], v[194:197], v[130:133]
	v_mfma_f32_16x16x32_f16 v[116:119], v[156:159], v[202:205], v[116:119]
	v_mfma_f32_16x16x32_f16 v[112:115], v[186:189], v[202:205], v[112:115]
	v_mfma_f32_16x16x32_f16 v[100:103], v[156:159], v[210:213], v[100:103]
	v_mfma_f32_16x16x32_f16 v[96:99], v[186:189], v[210:213], v[96:99]
	v_mfma_f32_16x16x32_f16 v[84:87], v[156:159], v[218:221], v[84:87]
	v_mfma_f32_16x16x32_f16 v[80:83], v[186:189], v[218:221], v[80:83]
	v_mfma_f32_16x16x32_f16 v[134:137], v[168:171], v[198:201], v[134:137]
	v_mfma_f32_16x16x32_f16 v[130:133], v[190:193], v[198:201], v[130:133]
	v_mfma_f32_16x16x32_f16 v[116:119], v[168:171], v[206:209], v[116:119]
	v_mfma_f32_16x16x32_f16 v[112:115], v[190:193], v[206:209], v[112:115]
	v_mfma_f32_16x16x32_f16 v[100:103], v[168:171], v[214:217], v[100:103]
	v_mfma_f32_16x16x32_f16 v[96:99], v[190:193], v[214:217], v[96:99]
	v_mfma_f32_16x16x32_f16 v[84:87], v[168:171], v[222:225], v[84:87]
	v_mfma_f32_16x16x32_f16 v[80:83], v[190:193], v[222:225], v[80:83]
	s_setprio 0
	s_barrier
	s_add_u32 s98, s56, s16
	s_addc_u32 s99, s57, s17
	s_add_u32 s100, s58, s16
	s_addc_u32 s101, s59, s17
	s_add_i32 s62, s62, s8
	s_mov_b32 m0, s62
	ds_read_b128 v[194:197], v165 offset:16384
	ds_read_b128 v[198:201], v165 offset:17408
	ds_read_b128 v[202:205], v165 offset:18432
	ds_read_b128 v[206:209], v165 offset:19456
	ds_read_b128 v[210:213], v165 offset:20480
	ds_read_b128 v[214:217], v165 offset:21504
	ds_read_b128 v[218:221], v165 offset:22528
	ds_read_b128 v[222:225], v165 offset:23552
	global_load_lds_dwordx4 v128, s[56:57]
	s_add_i32 m0, s62, 0x2000
	s_add_u32 s62, s56, 0x40000
	s_addc_u32 s63, s57, 0
	s_add_i32 s64, s64, s8
	global_load_lds_dwordx4 v146, s[56:57]
	s_mov_b32 m0, s64
	s_nop 0
	global_load_lds_dwordx4 v128, s[62:63]
	s_add_i32 m0, s64, 0x2000
	s_nop 0
	global_load_lds_dwordx4 v146, s[62:63]
	s_mov_b32 m0, s9
	s_nop 0
	global_load_lds_dwordx4 v150, s[58:59]
	s_mov_b32 m0, s10
	s_nop 0
	global_load_lds_dwordx4 v148, s[58:59]
	s_waitcnt vmcnt(8)
	s_waitcnt lgkmcnt(0)
	s_barrier
	s_setprio 1
	s_waitcnt lgkmcnt(0)
	v_mfma_f32_16x16x32_f16 v[76:79], v[32:35], v[194:197], v[76:79]
	v_mfma_f32_16x16x32_f16 v[72:75], v[40:43], v[194:197], v[72:75]
	v_mfma_f32_16x16x32_f16 v[60:63], v[32:35], v[202:205], v[60:63]
	v_mfma_f32_16x16x32_f16 v[56:59], v[40:43], v[202:205], v[56:59]
	v_mfma_f32_16x16x32_f16 v[28:31], v[32:35], v[210:213], v[28:31]
	v_mfma_f32_16x16x32_f16 v[24:27], v[40:43], v[210:213], v[24:27]
	v_mfma_f32_16x16x32_f16 v[12:15], v[32:35], v[218:221], v[12:15]
	v_mfma_f32_16x16x32_f16 v[8:11], v[40:43], v[218:221], v[8:11]
	v_mfma_f32_16x16x32_f16 v[76:79], v[36:39], v[198:201], v[76:79]
	v_mfma_f32_16x16x32_f16 v[72:75], v[44:47], v[198:201], v[72:75]
	v_mfma_f32_16x16x32_f16 v[60:63], v[36:39], v[206:209], v[60:63]
	v_mfma_f32_16x16x32_f16 v[56:59], v[44:47], v[206:209], v[56:59]
	v_mfma_f32_16x16x32_f16 v[28:31], v[36:39], v[214:217], v[28:31]
	v_mfma_f32_16x16x32_f16 v[24:27], v[44:47], v[214:217], v[24:27]
	v_mfma_f32_16x16x32_f16 v[12:15], v[36:39], v[222:225], v[12:15]
	v_mfma_f32_16x16x32_f16 v[8:11], v[44:47], v[222:225], v[8:11]
	v_mfma_f32_16x16x32_f16 v[20:23], v[156:159], v[210:213], v[20:23]
	v_mfma_f32_16x16x32_f16 v[16:19], v[186:189], v[210:213], v[16:19]
	v_mfma_f32_16x16x32_f16 v[4:7], v[156:159], v[218:221], v[4:7]
	v_mfma_f32_16x16x32_f16 v[0:3], v[186:189], v[218:221], v[0:3]
	v_mfma_f32_16x16x32_f16 v[32:35], v[156:159], v[194:197], v[68:71]
	v_mfma_f32_16x16x32_f16 v[36:39], v[186:189], v[194:197], v[64:67]
	v_mfma_f32_16x16x32_f16 v[40:43], v[156:159], v[202:205], v[52:55]
	v_mfma_f32_16x16x32_f16 v[44:47], v[186:189], v[202:205], v[48:51]
	v_mfma_f32_16x16x32_f16 v[20:23], v[168:171], v[214:217], v[20:23]
	v_mfma_f32_16x16x32_f16 v[16:19], v[190:193], v[214:217], v[16:19]
	v_mfma_f32_16x16x32_f16 v[4:7], v[168:171], v[222:225], v[4:7]
	v_mfma_f32_16x16x32_f16 v[0:3], v[190:193], v[222:225], v[0:3]
	v_mfma_f32_16x16x32_f16 v[32:35], v[168:171], v[198:201], v[32:35]
	v_mfma_f32_16x16x32_f16 v[36:39], v[190:193], v[198:201], v[36:39]
	v_mfma_f32_16x16x32_f16 v[40:43], v[168:171], v[206:209], v[40:43]
	v_mfma_f32_16x16x32_f16 v[44:47], v[190:193], v[206:209], v[44:47]
	s_setprio 0
	s_barrier
; #define PG8_STAGE(bufoff, gbase, voff) do { _Pragma("unroll") for (int _i = 0; _i < 2; ++_i) \
;         __builtin_amdgcn_global_load_lds((const unsigned*)((const char*)(gbase) + (voff)[_i]), (PG8_LAS unsigned*)(lds + (bufoff) + ldsw + _i * 8192), 16, 0, 0); } while (0)
; #define PG8_LDA(dst, b, h) do { _Pragma("unroll") for (int m = 0; m < 4; ++m) _Pragma("unroll") for (int k = 0; k < 2; ++k) dst[m][k] = *(const PG8_LAS bf16x8*)(lds + PG8_SA(b, h) + aoff + m * 2048 + k * 1024); } while (0)
; #define PG8_LDB(dst, b, h) do { _Pragma("unroll") for (int n = 0; n < 2; ++n) _Pragma("unroll") for (int k = 0; k < 2; ++k) dst[n][k] = *(const PG8_LAS bf16x8*)(lds + PG8_SB(b, h) + boff + n * 2048 + k * 1024); } while (0)
; #define PG8_MMA(ai, bj, At, Bt) do { __builtin_amdgcn_s_setprio(1); _Pragma("unroll") for (int m = 0; m < 4; ++m) _Pragma("unroll") for (int n = 0; n < 2; ++n) _Pragma("unroll") for (int k = 0; k < 2; ++k) \
;         acc[ai][bj][m][n] = mma16<F16>(Bt[n][k], At[m][k], acc[ai][bj][m][n]); __builtin_amdgcn_s_setprio(0); } while (0)
; #define PG8_WAIT_V(n) asm volatile("s_waitcnt vmcnt(" #n ")" ::: "memory")
; #define PG8_WAIT_L(n) asm volatile("s_waitcnt lgkmcnt(" #n ")" ::: "memory")
; #define PG8_BAR __builtin_amdgcn_s_barrier()
; #define PG8_SCHED __builtin_amdgcn_sched_barrier(0)
; template <class Epi, class Sched, bool ALIGN_EPI = false, bool SP2 = false, bool F16 = false>
; __device__ __forceinline__ void gemm_phase(PG8_LAS unsigned char* lds, const Gemm g, const Sched& S, const Epi& E) {
;     ...
;             PG8_LDB(B0, 1, 0); PG8_LDB(B1, 1, 1); PG8_SCHED; PG8_LDA(At, 1, 0); PG8_STAGE(PG8_SA(0, 1), a2 + hstep, voffA);
;             PG8_WAIT_V(8); PG8_WAIT_L(0); PG8_BAR; PG8_MMA(0, 0, At, B0); PG8_MMA(0, 1, At, B1); PG8_BAR; PG8_SCHED;
;             PG8_LDA(At, 1, 1); PG8_STAGE(PG8_SB(1, 0), b3, voffB); PG8_STAGE(PG8_SB(1, 1), b3 + hstep, voffB); PG8_STAGE(PG8_SA(1, 0), a3, voffA);
;             PG8_WAIT_V(8); PG8_WAIT_L(0); PG8_BAR; PG8_MMA(1, 0, At, B0); PG8_MMA(1, 1, At, B1); PG8_BAR; PG8_SCHED;
	s_add_i32 s62, 0, 0x18000
	s_add_i32 s63, 0, 0x1c000
	ds_read_b128 v[48:51], v172 offset:32768
	ds_read_b128 v[52:55], v172 offset:33792
	ds_read_b128 v[64:67], v172 offset:34816
	ds_read_b128 v[68:71], v172 offset:35840
	ds_read_b128 v[156:159], v172 offset:49152
	ds_read_b128 v[168:171], v172 offset:50176
	ds_read_b128 v[186:189], v172 offset:51200
	ds_read_b128 v[190:193], v172 offset:52224
	s_add_u32 s58, s58, 0x40000
	s_addc_u32 s59, s59, 0
	s_mov_b32 m0, s11
	ds_read_b128 v[194:197], v165 offset:32768
	ds_read_b128 v[198:201], v165 offset:33792
	ds_read_b128 v[202:205], v165 offset:34816
	ds_read_b128 v[206:209], v165 offset:35840
	ds_read_b128 v[210:213], v165 offset:36864
	ds_read_b128 v[214:217], v165 offset:37888
	ds_read_b128 v[218:221], v165 offset:38912
	ds_read_b128 v[222:225], v165 offset:39936
	global_load_lds_dwordx4 v150, s[58:59]
	s_mov_b32 m0, s13
	s_nop 0
	global_load_lds_dwordx4 v148, s[58:59]
	s_waitcnt vmcnt(8)
	s_waitcnt lgkmcnt(0)
	s_barrier
	s_setprio 1
	s_waitcnt lgkmcnt(0)
	v_mfma_f32_16x16x32_f16 v[142:145], v[48:51], v[194:197], v[142:145]
	v_mfma_f32_16x16x32_f16 v[138:141], v[64:67], v[194:197], v[138:141]
	v_mfma_f32_16x16x32_f16 v[124:127], v[48:51], v[202:205], v[124:127]
	v_mfma_f32_16x16x32_f16 v[120:123], v[64:67], v[202:205], v[120:123]
	v_mfma_f32_16x16x32_f16 v[108:111], v[48:51], v[210:213], v[108:111]
	v_mfma_f32_16x16x32_f16 v[104:107], v[64:67], v[210:213], v[104:107]
	v_mfma_f32_16x16x32_f16 v[92:95], v[48:51], v[218:221], v[92:95]
	v_mfma_f32_16x16x32_f16 v[88:91], v[64:67], v[218:221], v[88:91]
	v_mfma_f32_16x16x32_f16 v[142:145], v[52:55], v[198:201], v[142:145]
	v_mfma_f32_16x16x32_f16 v[138:141], v[68:71], v[198:201], v[138:141]
	v_mfma_f32_16x16x32_f16 v[124:127], v[52:55], v[206:209], v[124:127]
	v_mfma_f32_16x16x32_f16 v[120:123], v[68:71], v[206:209], v[120:123]
	v_mfma_f32_16x16x32_f16 v[108:111], v[52:55], v[214:217], v[108:111]
	v_mfma_f32_16x16x32_f16 v[104:107], v[68:71], v[214:217], v[104:107]
	v_mfma_f32_16x16x32_f16 v[92:95], v[52:55], v[222:225], v[92:95]
	v_mfma_f32_16x16x32_f16 v[88:91], v[68:71], v[222:225], v[88:91]
	v_mfma_f32_16x16x32_f16 v[134:137], v[156:159], v[194:197], v[134:137]
	v_mfma_f32_16x16x32_f16 v[130:133], v[186:189], v[194:197], v[130:133]
	v_mfma_f32_16x16x32_f16 v[116:119], v[156:159], v[202:205], v[116:119]
	v_mfma_f32_16x16x32_f16 v[112:115], v[186:189], v[202:205], v[112:115]
	v_mfma_f32_16x16x32_f16 v[100:103], v[156:159], v[210:213], v[100:103]
	v_mfma_f32_16x16x32_f16 v[96:99], v[186:189], v[210:213], v[96:99]
	v_mfma_f32_16x16x32_f16 v[84:87], v[156:159], v[218:221], v[84:87]
	v_mfma_f32_16x16x32_f16 v[80:83], v[186:189], v[218:221], v[80:83]
	v_mfma_f32_16x16x32_f16 v[134:137], v[168:171], v[198:201], v[134:137]
	v_mfma_f32_16x16x32_f16 v[130:133], v[190:193], v[198:201], v[130:133]
	v_mfma_f32_16x16x32_f16 v[116:119], v[168:171], v[206:209], v[116:119]
	v_mfma_f32_16x16x32_f16 v[112:115], v[190:193], v[206:209], v[112:115]
	v_mfma_f32_16x16x32_f16 v[100:103], v[168:171], v[214:217], v[100:103]
	v_mfma_f32_16x16x32_f16 v[96:99], v[190:193], v[214:217], v[96:99]
	v_mfma_f32_16x16x32_f16 v[84:87], v[168:171], v[222:225], v[84:87]
	v_mfma_f32_16x16x32_f16 v[80:83], v[190:193], v[222:225], v[80:83]
	s_setprio 0
	s_barrier
	s_add_i32 s58, s62, s8
	s_mov_b32 m0, s58
	ds_read_b128 v[194:197], v165 offset:49152
	ds_read_b128 v[198:201], v165 offset:50176
	ds_read_b128 v[202:205], v165 offset:51200
	ds_read_b128 v[206:209], v165 offset:52224
	ds_read_b128 v[210:213], v165 offset:53248
	ds_read_b128 v[214:217], v165 offset:54272
	ds_read_b128 v[218:221], v165 offset:55296
	ds_read_b128 v[222:225], v165 offset:56320
	global_load_lds_dwordx4 v128, s[98:99]
	s_add_i32 m0, s58, 0x2000
	s_add_u32 s56, s56, 0x40080
	s_addc_u32 s57, s57, 0
	s_add_i32 s58, s63, s8
	global_load_lds_dwordx4 v146, s[98:99]
	s_mov_b32 m0, s58
	s_nop 0
	global_load_lds_dwordx4 v128, s[56:57]
	s_add_i32 m0, s58, 0x2000
	s_nop 0
	global_load_lds_dwordx4 v146, s[56:57]
	s_mov_b32 m0, s20
	s_nop 0
	global_load_lds_dwordx4 v150, s[100:101]
	s_mov_b32 m0, s21
	s_nop 0
	global_load_lds_dwordx4 v148, s[100:101]
	s_waitcnt vmcnt(8)
	s_waitcnt lgkmcnt(0)
	s_barrier
	s_setprio 1
	s_waitcnt lgkmcnt(0)
	v_mfma_f32_16x16x32_f16 v[76:79], v[48:51], v[194:197], v[76:79]
	v_mfma_f32_16x16x32_f16 v[72:75], v[64:67], v[194:197], v[72:75]
	v_mfma_f32_16x16x32_f16 v[60:63], v[48:51], v[202:205], v[60:63]
	v_mfma_f32_16x16x32_f16 v[56:59], v[64:67], v[202:205], v[56:59]
	v_mfma_f32_16x16x32_f16 v[28:31], v[48:51], v[210:213], v[28:31]
	v_mfma_f32_16x16x32_f16 v[24:27], v[64:67], v[210:213], v[24:27]
	v_mfma_f32_16x16x32_f16 v[12:15], v[48:51], v[218:221], v[12:15]
	v_mfma_f32_16x16x32_f16 v[8:11], v[64:67], v[218:221], v[8:11]
	v_mfma_f32_16x16x32_f16 v[76:79], v[52:55], v[198:201], v[76:79]
	v_mfma_f32_16x16x32_f16 v[72:75], v[68:71], v[198:201], v[72:75]
	v_mfma_f32_16x16x32_f16 v[60:63], v[52:55], v[206:209], v[60:63]
	v_mfma_f32_16x16x32_f16 v[56:59], v[68:71], v[206:209], v[56:59]
	v_mfma_f32_16x16x32_f16 v[28:31], v[52:55], v[214:217], v[28:31]
	v_mfma_f32_16x16x32_f16 v[24:27], v[68:71], v[214:217], v[24:27]
	v_mfma_f32_16x16x32_f16 v[12:15], v[52:55], v[222:225], v[12:15]
	v_mfma_f32_16x16x32_f16 v[8:11], v[68:71], v[222:225], v[8:11]
	v_mfma_f32_16x16x32_f16 v[32:35], v[156:159], v[194:197], v[32:35]
	v_mfma_f32_16x16x32_f16 v[68:71], v[168:171], v[198:201], v[32:35]
	v_mfma_f32_16x16x32_f16 v[32:35], v[186:189], v[194:197], v[36:39]
	v_mfma_f32_16x16x32_f16 v[64:67], v[190:193], v[198:201], v[32:35]
	v_mfma_f32_16x16x32_f16 v[32:35], v[156:159], v[202:205], v[40:43]
	v_mfma_f32_16x16x32_f16 v[52:55], v[168:171], v[206:209], v[32:35]
	v_mfma_f32_16x16x32_f16 v[32:35], v[186:189], v[202:205], v[44:47]
	v_mfma_f32_16x16x32_f16 v[20:23], v[156:159], v[210:213], v[20:23]
	v_mfma_f32_16x16x32_f16 v[16:19], v[186:189], v[210:213], v[16:19]
	v_mfma_f32_16x16x32_f16 v[4:7], v[156:159], v[218:221], v[4:7]
	v_mfma_f32_16x16x32_f16 v[0:3], v[186:189], v[218:221], v[0:3]
	v_mfma_f32_16x16x32_f16 v[48:51], v[190:193], v[206:209], v[32:35]
	v_mfma_f32_16x16x32_f16 v[20:23], v[168:171], v[214:217], v[20:23]
	v_mfma_f32_16x16x32_f16 v[16:19], v[190:193], v[214:217], v[16:19]
	v_mfma_f32_16x16x32_f16 v[4:7], v[168:171], v[222:225], v[4:7]
	v_mfma_f32_16x16x32_f16 v[0:3], v[190:193], v[222:225], v[0:3]
	s_setprio 0
	s_barrier
	s_add_i32 s61, s61, 2
	s_add_u32 s54, s54, 0x100
	s_addc_u32 s55, s55, 0
	s_add_u32 s49, s49, 0x100
	s_addc_u32 s60, s60, 0
	s_cmp_gt_u32 s61, 13
	s_cbranch_scc0 .LBB0_904
	s_and_b64 vcc, exec, s[44:45]
	s_cbranch_vccz .LBB0_907
	s_barrier

; #define PG8_STAGE(bufoff, gbase, voff) do { _Pragma("unroll") for (int _i = 0; _i < 2; ++_i) \
;         __builtin_amdgcn_global_load_lds((const unsigned*)((const char*)(gbase) + (voff)[_i]), (PG8_LAS unsigned*)(lds + (bufoff) + ldsw + _i * 8192), 16, 0, 0); } while (0)
; #define PG8_LDA(dst, b, h) do { _Pragma("unroll") for (int m = 0; m < 4; ++m) _Pragma("unroll") for (int k = 0; k < 2; ++k) dst[m][k] = *(const PG8_LAS bf16x8*)(lds + PG8_SA(b, h) + aoff + m * 2048 + k * 1024); } while (0)
; #define PG8_LDB(dst, b, h) do { _Pragma("unroll") for (int n = 0; n < 2; ++n) _Pragma("unroll") for (int k = 0; k < 2; ++k) dst[n][k] = *(const PG8_LAS bf16x8*)(lds + PG8_SB(b, h) + boff + n * 2048 + k * 1024); } while (0)
; #define PG8_MMA(ai, bj, At, Bt) do { __builtin_amdgcn_s_setprio(1); _Pragma("unroll") for (int m = 0; m < 4; ++m) _Pragma("unroll") for (int n = 0; n < 2; ++n) _Pragma("unroll") for (int k = 0; k < 2; ++k) \
;         acc[ai][bj][m][n] = mma16<F16>(Bt[n][k], At[m][k], acc[ai][bj][m][n]); __builtin_amdgcn_s_setprio(0); } while (0)
; #define PG8_WAIT_V(n) asm volatile("s_waitcnt vmcnt(" #n ")" ::: "memory")
; #define PG8_WAIT_L(n) asm volatile("s_waitcnt lgkmcnt(" #n ")" ::: "memory")
; #define PG8_BAR __builtin_amdgcn_s_barrier()
; #define PG8_SCHED __builtin_amdgcn_sched_barrier(0)
; template <class Epi, class Sched, bool ALIGN_EPI = false, bool SP2 = false, bool F16 = false>
; __device__ __forceinline__ void gemm_phase(PG8_LAS unsigned char* lds, const Gemm g, const Sched& S, const Epi& E) {
;     ...
;             const char* a1 = cA + (size_t)(t + 1) * kstep;
;             const char* a2 = last ? nA : cA + (size_t)(t + 2) * kstep; const char* b2 = last ? nB : cB + (size_t)(t + 2) * kstep;
;             const char* a3 = a2 + kstep; const char* b3 = b2 + kstep;
;             if (last && has_next) S.a_ready(nxt);
;             if constexpr (SP2) {
;             PG8_LDB(B0, 0, 0); PG8_LDB(B1, 0, 1); PG8_SCHED; PG8_LDA(At, 0, 0); PG8_STAGE(PG8_SA(1, 1), a1 + hstep, voffA);
;             PG8_WAIT_V(8); PG8_WAIT_L(0); PG8_BAR; PG8_MMA(0, 0, At, B0); PG8_MMA(0, 1, At, B1); PG8_BAR; PG8_SCHED;
;             PG8_LDA(At, 0, 1); PG8_STAGE(PG8_SB(0, 0), b2, voffB); PG8_STAGE(PG8_SB(0, 1), b2 + hstep, voffB); PG8_STAGE(PG8_SA(0, 0), a2, voffA);
;             PG8_WAIT_V(8); PG8_WAIT_L(0); PG8_BAR; PG8_MMA(1, 0, At, B0); PG8_MMA(1, 1, At, B1); PG8_BAR; PG8_SCHED;
.LBB0_997:
	s_add_u32 s50, s48, 0x100
	s_addc_u32 s51, s49, 0
	s_add_i32 s59, 0, 0x10000
	s_cmp_eq_u32 s58, 40
	s_cselect_b32 s55, s43, s51
	s_cselect_b32 s54, s42, s50
	s_cselect_b32 s53, s47, s5
	s_cselect_b32 s52, s46, s4
	s_add_i32 s60, 0, 0x14000
	ds_read_b128 v[130:133], v172
	ds_read_b128 v[134:137], v172 offset:1024
	ds_read_b128 v[138:141], v172 offset:2048
	ds_read_b128 v[142:145], v172 offset:3072
	ds_read_b128 v[146:149], v172 offset:16384
	ds_read_b128 v[150:153], v172 offset:17408
	ds_read_b128 v[154:157], v172 offset:18432
	ds_read_b128 v[158:161], v172 offset:19456
	s_add_i32 m0, s9, 0xc000
	ds_read_b128 v[186:189], v225
	ds_read_b128 v[190:193], v225 offset:1024
	ds_read_b128 v[194:197], v225 offset:2048
	ds_read_b128 v[198:201], v225 offset:3072
	ds_read_b128 v[202:205], v225 offset:4096
	ds_read_b128 v[206:209], v225 offset:5120
	ds_read_b128 v[210:213], v225 offset:6144
	ds_read_b128 v[214:217], v225 offset:7168
	global_load_lds_dwordx4 v168, s[48:49]
	s_add_i32 m0, s9, 0xe000
	s_nop 0
	global_load_lds_dwordx4 v170, s[48:49]
	s_waitcnt vmcnt(8)
	s_waitcnt lgkmcnt(0)
	s_barrier
	s_setprio 1
	s_waitcnt lgkmcnt(0)
	v_mfma_f32_16x16x32_bf16 v[124:127], v[130:133], v[186:189], v[124:127]
	v_mfma_f32_16x16x32_bf16 v[120:123], v[138:141], v[186:189], v[120:123]
	v_mfma_f32_16x16x32_bf16 v[116:119], v[130:133], v[194:197], v[116:119]
	v_mfma_f32_16x16x32_bf16 v[112:115], v[138:141], v[194:197], v[112:115]
	v_mfma_f32_16x16x32_bf16 v[108:111], v[130:133], v[202:205], v[108:111]
	v_mfma_f32_16x16x32_bf16 v[104:107], v[138:141], v[202:205], v[104:107]
	v_mfma_f32_16x16x32_bf16 v[100:103], v[130:133], v[210:213], v[100:103]
	v_mfma_f32_16x16x32_bf16 v[96:99], v[138:141], v[210:213], v[96:99]
	v_mfma_f32_16x16x32_bf16 v[124:127], v[134:137], v[190:193], v[124:127]
	v_mfma_f32_16x16x32_bf16 v[120:123], v[142:145], v[190:193], v[120:123]
	v_mfma_f32_16x16x32_bf16 v[116:119], v[134:137], v[198:201], v[116:119]
	v_mfma_f32_16x16x32_bf16 v[112:115], v[142:145], v[198:201], v[112:115]
	v_mfma_f32_16x16x32_bf16 v[108:111], v[134:137], v[206:209], v[108:111]
	v_mfma_f32_16x16x32_bf16 v[104:107], v[142:145], v[206:209], v[104:107]
	v_mfma_f32_16x16x32_bf16 v[100:103], v[134:137], v[214:217], v[100:103]
	v_mfma_f32_16x16x32_bf16 v[96:99], v[142:145], v[214:217], v[96:99]
	v_mfma_f32_16x16x32_bf16 v[60:63], v[146:149], v[186:189], v[60:63]
	v_mfma_f32_16x16x32_bf16 v[56:59], v[154:157], v[186:189], v[56:59]
	v_mfma_f32_16x16x32_bf16 v[52:55], v[146:149], v[194:197], v[52:55]
	v_mfma_f32_16x16x32_bf16 v[48:51], v[154:157], v[194:197], v[48:51]
	v_mfma_f32_16x16x32_bf16 v[44:47], v[146:149], v[202:205], v[44:47]
	v_mfma_f32_16x16x32_bf16 v[40:43], v[154:157], v[202:205], v[40:43]
	v_mfma_f32_16x16x32_bf16 v[36:39], v[146:149], v[210:213], v[36:39]
	v_mfma_f32_16x16x32_bf16 v[32:35], v[154:157], v[210:213], v[32:35]
	v_mfma_f32_16x16x32_bf16 v[60:63], v[150:153], v[190:193], v[60:63]
	v_mfma_f32_16x16x32_bf16 v[56:59], v[158:161], v[190:193], v[56:59]
	v_mfma_f32_16x16x32_bf16 v[52:55], v[150:153], v[198:201], v[52:55]
	v_mfma_f32_16x16x32_bf16 v[48:51], v[158:161], v[198:201], v[48:51]
	v_mfma_f32_16x16x32_bf16 v[44:47], v[150:153], v[206:209], v[44:47]
	v_mfma_f32_16x16x32_bf16 v[40:43], v[158:161], v[206:209], v[40:43]
	v_mfma_f32_16x16x32_bf16 v[36:39], v[150:153], v[214:217], v[36:39]
	v_mfma_f32_16x16x32_bf16 v[32:35], v[158:161], v[214:217], v[32:35]
	s_setprio 0
	s_barrier
	s_add_u32 s98, s52, s16
	s_addc_u32 s99, s53, s17
	s_add_u32 s100, s54, s16
	s_addc_u32 s101, s55, s17
	s_add_i32 s48, s59, s8
	s_mov_b32 m0, s48
	ds_read_b128 v[186:189], v225 offset:16384
	ds_read_b128 v[190:193], v225 offset:17408
	ds_read_b128 v[194:197], v225 offset:18432
	ds_read_b128 v[198:201], v225 offset:19456
	ds_read_b128 v[202:205], v225 offset:20480
	ds_read_b128 v[206:209], v225 offset:21504
	ds_read_b128 v[210:213], v225 offset:22528
	ds_read_b128 v[214:217], v225 offset:23552
	global_load_lds_dwordx4 v128, s[52:53]
	s_add_i32 m0, s48, 0x2000
	s_add_u32 s48, s52, 0xb0000
	s_addc_u32 s49, s53, 0
	s_add_i32 s59, s60, s8
	global_load_lds_dwordx4 v162, s[52:53]
	s_mov_b32 m0, s59
	s_nop 0
	global_load_lds_dwordx4 v128, s[48:49]
	s_add_i32 m0, s59, 0x2000
	s_nop 0
	global_load_lds_dwordx4 v162, s[48:49]
	s_mov_b32 m0, s9
	s_nop 0
	global_load_lds_dwordx4 v166, s[54:55]
	s_mov_b32 m0, s10
	s_nop 0
	global_load_lds_dwordx4 v164, s[54:55]
	s_waitcnt vmcnt(8)
	s_waitcnt lgkmcnt(0)
	s_barrier
	s_setprio 1
	s_waitcnt lgkmcnt(0)
	v_mfma_f32_16x16x32_bf16 v[92:95], v[130:133], v[186:189], v[92:95]
	v_mfma_f32_16x16x32_bf16 v[88:91], v[138:141], v[186:189], v[88:91]
	v_mfma_f32_16x16x32_bf16 v[84:87], v[130:133], v[194:197], v[84:87]
	v_mfma_f32_16x16x32_bf16 v[80:83], v[138:141], v[194:197], v[80:83]
	v_mfma_f32_16x16x32_bf16 v[76:79], v[130:133], v[202:205], v[76:79]
	v_mfma_f32_16x16x32_bf16 v[72:75], v[138:141], v[202:205], v[72:75]
	v_mfma_f32_16x16x32_bf16 v[68:71], v[130:133], v[210:213], v[68:71]
	v_mfma_f32_16x16x32_bf16 v[64:67], v[138:141], v[210:213], v[64:67]
	v_mfma_f32_16x16x32_bf16 v[92:95], v[134:137], v[190:193], v[92:95]
	v_mfma_f32_16x16x32_bf16 v[88:91], v[142:145], v[190:193], v[88:91]
	v_mfma_f32_16x16x32_bf16 v[84:87], v[134:137], v[198:201], v[84:87]
	v_mfma_f32_16x16x32_bf16 v[80:83], v[142:145], v[198:201], v[80:83]
	v_mfma_f32_16x16x32_bf16 v[76:79], v[134:137], v[206:209], v[76:79]
	v_mfma_f32_16x16x32_bf16 v[72:75], v[142:145], v[206:209], v[72:75]
	v_mfma_f32_16x16x32_bf16 v[68:71], v[134:137], v[214:217], v[68:71]
	v_mfma_f32_16x16x32_bf16 v[64:67], v[142:145], v[214:217], v[64:67]
	v_mfma_f32_16x16x32_bf16 v[28:31], v[146:149], v[186:189], v[28:31]
	v_mfma_f32_16x16x32_bf16 v[24:27], v[154:157], v[186:189], v[24:27]
	v_mfma_f32_16x16x32_bf16 v[20:23], v[146:149], v[194:197], v[20:23]
	v_mfma_f32_16x16x32_bf16 v[16:19], v[154:157], v[194:197], v[16:19]
	v_mfma_f32_16x16x32_bf16 v[12:15], v[146:149], v[202:205], v[12:15]
	v_mfma_f32_16x16x32_bf16 v[8:11], v[154:157], v[202:205], v[8:11]
	v_mfma_f32_16x16x32_bf16 v[4:7], v[146:149], v[210:213], v[4:7]
	v_mfma_f32_16x16x32_bf16 v[0:3], v[154:157], v[210:213], v[0:3]
	v_mfma_f32_16x16x32_bf16 v[28:31], v[150:153], v[190:193], v[28:31]
	v_mfma_f32_16x16x32_bf16 v[24:27], v[158:161], v[190:193], v[24:27]
	v_mfma_f32_16x16x32_bf16 v[20:23], v[150:153], v[198:201], v[20:23]
	v_mfma_f32_16x16x32_bf16 v[16:19], v[158:161], v[198:201], v[16:19]
	v_mfma_f32_16x16x32_bf16 v[12:15], v[150:153], v[206:209], v[12:15]
	v_mfma_f32_16x16x32_bf16 v[8:11], v[158:161], v[206:209], v[8:11]
	v_mfma_f32_16x16x32_bf16 v[4:7], v[150:153], v[214:217], v[4:7]
	v_mfma_f32_16x16x32_bf16 v[0:3], v[158:161], v[214:217], v[0:3]
	s_setprio 0
	s_barrier
; #define PG8_STAGE(bufoff, gbase, voff) do { _Pragma("unroll") for (int _i = 0; _i < 2; ++_i) \
;         __builtin_amdgcn_global_load_lds((const unsigned*)((const char*)(gbase) + (voff)[_i]), (PG8_LAS unsigned*)(lds + (bufoff) + ldsw + _i * 8192), 16, 0, 0); } while (0)
; #define PG8_LDA(dst, b, h) do { _Pragma("unroll") for (int m = 0; m < 4; ++m) _Pragma("unroll") for (int k = 0; k < 2; ++k) dst[m][k] = *(const PG8_LAS bf16x8*)(lds + PG8_SA(b, h) + aoff + m * 2048 + k * 1024); } while (0)
; #define PG8_LDB(dst, b, h) do { _Pragma("unroll") for (int n = 0; n < 2; ++n) _Pragma("unroll") for (int k = 0; k < 2; ++k) dst[n][k] = *(const PG8_LAS bf16x8*)(lds + PG8_SB(b, h) + boff + n * 2048 + k * 1024); } while (0)
; #define PG8_MMA(ai, bj, At, Bt) do { __builtin_amdgcn_s_setprio(1); _Pragma("unroll") for (int m = 0; m < 4; ++m) _Pragma("unroll") for (int n = 0; n < 2; ++n) _Pragma("unroll") for (int k = 0; k < 2; ++k) \
;         acc[ai][bj][m][n] = mma16<F16>(Bt[n][k], At[m][k], acc[ai][bj][m][n]); __builtin_amdgcn_s_setprio(0); } while (0)
; #define PG8_WAIT_V(n) asm volatile("s_waitcnt vmcnt(" #n ")" ::: "memory")
; #define PG8_WAIT_L(n) asm volatile("s_waitcnt lgkmcnt(" #n ")" ::: "memory")
; #define PG8_BAR __builtin_amdgcn_s_barrier()
; #define PG8_SCHED __builtin_amdgcn_sched_barrier(0)
; template <class Epi, class Sched, bool ALIGN_EPI = false, bool SP2 = false, bool F16 = false>
; __device__ __forceinline__ void gemm_phase(PG8_LAS unsigned char* lds, const Gemm g, const Sched& S, const Epi& E) {
;     ...
;             PG8_LDB(B0, 1, 0); PG8_LDB(B1, 1, 1); PG8_SCHED; PG8_LDA(At, 1, 0); PG8_STAGE(PG8_SA(0, 1), a2 + hstep, voffA);
;             PG8_WAIT_V(8); PG8_WAIT_L(0); PG8_BAR; PG8_MMA(0, 0, At, B0); PG8_MMA(0, 1, At, B1); PG8_BAR; PG8_SCHED;
;             PG8_LDA(At, 1, 1); PG8_STAGE(PG8_SB(1, 0), b3, voffB); PG8_STAGE(PG8_SB(1, 1), b3 + hstep, voffB); PG8_STAGE(PG8_SA(1, 0), a3, voffA);
;             PG8_WAIT_V(8); PG8_WAIT_L(0); PG8_BAR; PG8_MMA(1, 0, At, B0); PG8_MMA(1, 1, At, B1); PG8_BAR; PG8_SCHED;
	s_add_i32 s59, 0, 0x18000
	s_add_i32 s60, 0, 0x1c000
	ds_read_b128 v[130:133], v172 offset:32768
	ds_read_b128 v[134:137], v172 offset:33792
	ds_read_b128 v[138:141], v172 offset:34816
	ds_read_b128 v[142:145], v172 offset:35840
	ds_read_b128 v[146:149], v172 offset:49152
	ds_read_b128 v[150:153], v172 offset:50176
	ds_read_b128 v[154:157], v172 offset:51200
	ds_read_b128 v[158:161], v172 offset:52224
	s_add_u32 s48, s54, 0xb0000
	s_addc_u32 s49, s55, 0
	s_mov_b32 m0, s11
	ds_read_b128 v[186:189], v225 offset:32768
	ds_read_b128 v[190:193], v225 offset:33792
	ds_read_b128 v[194:197], v225 offset:34816
	ds_read_b128 v[198:201], v225 offset:35840
	ds_read_b128 v[202:205], v225 offset:36864
	ds_read_b128 v[206:209], v225 offset:37888
	ds_read_b128 v[210:213], v225 offset:38912
	ds_read_b128 v[214:217], v225 offset:39936
	global_load_lds_dwordx4 v166, s[48:49]
	s_mov_b32 m0, s14
	s_nop 0
	global_load_lds_dwordx4 v164, s[48:49]
	s_waitcnt vmcnt(8)
	s_waitcnt lgkmcnt(0)
	s_barrier
	s_setprio 1
	s_waitcnt lgkmcnt(0)
	v_mfma_f32_16x16x32_bf16 v[124:127], v[130:133], v[186:189], v[124:127]
	v_mfma_f32_16x16x32_bf16 v[120:123], v[138:141], v[186:189], v[120:123]
	v_mfma_f32_16x16x32_bf16 v[116:119], v[130:133], v[194:197], v[116:119]
	v_mfma_f32_16x16x32_bf16 v[112:115], v[138:141], v[194:197], v[112:115]
	v_mfma_f32_16x16x32_bf16 v[108:111], v[130:133], v[202:205], v[108:111]
	v_mfma_f32_16x16x32_bf16 v[104:107], v[138:141], v[202:205], v[104:107]
	v_mfma_f32_16x16x32_bf16 v[100:103], v[130:133], v[210:213], v[100:103]
	v_mfma_f32_16x16x32_bf16 v[96:99], v[138:141], v[210:213], v[96:99]
	v_mfma_f32_16x16x32_bf16 v[124:127], v[134:137], v[190:193], v[124:127]
	v_mfma_f32_16x16x32_bf16 v[120:123], v[142:145], v[190:193], v[120:123]
	v_mfma_f32_16x16x32_bf16 v[116:119], v[134:137], v[198:201], v[116:119]
	v_mfma_f32_16x16x32_bf16 v[112:115], v[142:145], v[198:201], v[112:115]
	v_mfma_f32_16x16x32_bf16 v[108:111], v[134:137], v[206:209], v[108:111]
	v_mfma_f32_16x16x32_bf16 v[104:107], v[142:145], v[206:209], v[104:107]
	v_mfma_f32_16x16x32_bf16 v[100:103], v[134:137], v[214:217], v[100:103]
	v_mfma_f32_16x16x32_bf16 v[96:99], v[142:145], v[214:217], v[96:99]
	v_mfma_f32_16x16x32_bf16 v[60:63], v[146:149], v[186:189], v[60:63]
	v_mfma_f32_16x16x32_bf16 v[56:59], v[154:157], v[186:189], v[56:59]
	v_mfma_f32_16x16x32_bf16 v[52:55], v[146:149], v[194:197], v[52:55]
	v_mfma_f32_16x16x32_bf16 v[48:51], v[154:157], v[194:197], v[48:51]
	v_mfma_f32_16x16x32_bf16 v[44:47], v[146:149], v[202:205], v[44:47]
	v_mfma_f32_16x16x32_bf16 v[40:43], v[154:157], v[202:205], v[40:43]
	v_mfma_f32_16x16x32_bf16 v[36:39], v[146:149], v[210:213], v[36:39]
	v_mfma_f32_16x16x32_bf16 v[32:35], v[154:157], v[210:213], v[32:35]
	v_mfma_f32_16x16x32_bf16 v[60:63], v[150:153], v[190:193], v[60:63]
	v_mfma_f32_16x16x32_bf16 v[56:59], v[158:161], v[190:193], v[56:59]
	v_mfma_f32_16x16x32_bf16 v[52:55], v[150:153], v[198:201], v[52:55]
	v_mfma_f32_16x16x32_bf16 v[48:51], v[158:161], v[198:201], v[48:51]
	v_mfma_f32_16x16x32_bf16 v[44:47], v[150:153], v[206:209], v[44:47]
	v_mfma_f32_16x16x32_bf16 v[40:43], v[158:161], v[206:209], v[40:43]
	v_mfma_f32_16x16x32_bf16 v[36:39], v[150:153], v[214:217], v[36:39]
	v_mfma_f32_16x16x32_bf16 v[32:35], v[158:161], v[214:217], v[32:35]
	s_setprio 0
	s_barrier
	s_add_i32 s48, s59, s8
	s_mov_b32 m0, s48
	ds_read_b128 v[186:189], v225 offset:49152
	ds_read_b128 v[190:193], v225 offset:50176
	ds_read_b128 v[194:197], v225 offset:51200
	ds_read_b128 v[198:201], v225 offset:52224
	ds_read_b128 v[202:205], v225 offset:53248
	ds_read_b128 v[206:209], v225 offset:54272
	ds_read_b128 v[210:213], v225 offset:55296
	ds_read_b128 v[214:217], v225 offset:56320
	global_load_lds_dwordx4 v128, s[98:99]
	s_add_i32 m0, s48, 0x2000
	s_add_u32 s48, s52, 0xb0080
	s_addc_u32 s49, s53, 0
	s_add_i32 s52, s60, s8
	global_load_lds_dwordx4 v162, s[98:99]
	s_mov_b32 m0, s52
	s_nop 0
	global_load_lds_dwordx4 v128, s[48:49]
	s_add_i32 m0, s52, 0x2000
	s_nop 0
	global_load_lds_dwordx4 v162, s[48:49]
	s_mov_b32 m0, s29
	s_nop 0
	global_load_lds_dwordx4 v166, s[100:101]
	s_mov_b32 m0, s30
	s_nop 0
	global_load_lds_dwordx4 v164, s[100:101]
	s_waitcnt vmcnt(8)
	s_waitcnt lgkmcnt(0)
	s_barrier
	s_setprio 1
	s_waitcnt lgkmcnt(0)
	v_mfma_f32_16x16x32_bf16 v[92:95], v[130:133], v[186:189], v[92:95]
	v_mfma_f32_16x16x32_bf16 v[88:91], v[138:141], v[186:189], v[88:91]
	v_mfma_f32_16x16x32_bf16 v[84:87], v[130:133], v[194:197], v[84:87]
	v_mfma_f32_16x16x32_bf16 v[80:83], v[138:141], v[194:197], v[80:83]
	v_mfma_f32_16x16x32_bf16 v[76:79], v[130:133], v[202:205], v[76:79]
	v_mfma_f32_16x16x32_bf16 v[72:75], v[138:141], v[202:205], v[72:75]
	v_mfma_f32_16x16x32_bf16 v[68:71], v[130:133], v[210:213], v[68:71]
	v_mfma_f32_16x16x32_bf16 v[64:67], v[138:141], v[210:213], v[64:67]
	v_mfma_f32_16x16x32_bf16 v[92:95], v[134:137], v[190:193], v[92:95]
	v_mfma_f32_16x16x32_bf16 v[88:91], v[142:145], v[190:193], v[88:91]
	v_mfma_f32_16x16x32_bf16 v[84:87], v[134:137], v[198:201], v[84:87]
	v_mfma_f32_16x16x32_bf16 v[80:83], v[142:145], v[198:201], v[80:83]
	v_mfma_f32_16x16x32_bf16 v[76:79], v[134:137], v[206:209], v[76:79]
	v_mfma_f32_16x16x32_bf16 v[72:75], v[142:145], v[206:209], v[72:75]
	v_mfma_f32_16x16x32_bf16 v[68:71], v[134:137], v[214:217], v[68:71]
	v_mfma_f32_16x16x32_bf16 v[64:67], v[142:145], v[214:217], v[64:67]
	v_mfma_f32_16x16x32_bf16 v[28:31], v[146:149], v[186:189], v[28:31]
	v_mfma_f32_16x16x32_bf16 v[24:27], v[154:157], v[186:189], v[24:27]
	v_mfma_f32_16x16x32_bf16 v[20:23], v[146:149], v[194:197], v[20:23]
	v_mfma_f32_16x16x32_bf16 v[16:19], v[154:157], v[194:197], v[16:19]
	v_mfma_f32_16x16x32_bf16 v[12:15], v[146:149], v[202:205], v[12:15]
	v_mfma_f32_16x16x32_bf16 v[8:11], v[154:157], v[202:205], v[8:11]
	v_mfma_f32_16x16x32_bf16 v[4:7], v[146:149], v[210:213], v[4:7]
	v_mfma_f32_16x16x32_bf16 v[0:3], v[154:157], v[210:213], v[0:3]
	v_mfma_f32_16x16x32_bf16 v[28:31], v[150:153], v[190:193], v[28:31]
	v_mfma_f32_16x16x32_bf16 v[24:27], v[158:161], v[190:193], v[24:27]
	v_mfma_f32_16x16x32_bf16 v[20:23], v[150:153], v[198:201], v[20:23]
	v_mfma_f32_16x16x32_bf16 v[16:19], v[158:161], v[198:201], v[16:19]
	v_mfma_f32_16x16x32_bf16 v[12:15], v[150:153], v[206:209], v[12:15]
	v_mfma_f32_16x16x32_bf16 v[8:11], v[158:161], v[206:209], v[8:11]
	v_mfma_f32_16x16x32_bf16 v[4:7], v[150:153], v[214:217], v[4:7]
	v_mfma_f32_16x16x32_bf16 v[0:3], v[158:161], v[214:217], v[0:3]
	s_setprio 0
	s_barrier
	s_add_i32 s58, s58, 2
	s_add_u32 s4, s4, 0x100
	s_addc_u32 s5, s5, 0
	s_cmp_gt_u32 s58, 41
	s_mov_b64 s[48:49], s[50:51]
	s_cbranch_scc0 .LBB0_997
	s_and_b64 vcc, exec, s[44:45]
	s_cbranch_vccz .LBB0_1000
	s_barrier
